# MFMA order in every GEMM block: each accumulator's two k-step MFMAs issued back to back (accumulate chain of 2) instead of all k0 then all k1
# speedup vs baseline: 1.0128x; 1.0121x over previous
.LBB0_177:
	s_ashr_i32 s29, s28, 31
	s_lshl_b64 s[38:39], s[28:29], 19
	s_add_u32 s38, s84, s38
	s_addc_u32 s39, s85, s39
	s_and_b64 s[40:41], s[36:37], exec
	s_cselect_b32 s29, s39, s1
	s_cselect_b32 s62, s38, s0
	s_ashr_i32 s35, s34, 31
	s_lshl_b64 s[40:41], s[34:35], 19
	s_add_u32 s40, s16, s40
	s_addc_u32 s41, s17, s41
	s_and_b64 s[46:47], s[36:37], exec
	s_cselect_b32 s63, s41, s45
	s_cselect_b32 s64, s40, s44
	s_lshl_b32 s35, s30, 8
	s_add_u32 s65, s44, 0x100
	v_mov_b32_e32 v2, 0
	v_or_b32_e32 v134, s35, v172
	v_lshl_add_u64 v[130:131], s[0:1], 0, v[148:149]
	v_lshl_add_u64 v[132:133], s[0:1], 0, v[150:151]
	s_addc_u32 s66, s45, 0
	s_mov_b32 s67, -2
	s_mov_b64 s[30:31], 0
	s_waitcnt lgkmcnt(0)
	ds_read_b128 v[160:163], v240
	ds_read_b128 v[164:167], v240 offset:1024
	ds_read_b128 v[178:181], v240 offset:2048
	ds_read_b128 v[182:185], v240 offset:3072
	s_add_u32 s44, s0, s30
	ds_read_b128 v[186:189], v240 offset:16384
	ds_read_b128 v[190:193], v240 offset:17408
	ds_read_b128 v[194:197], v240 offset:18432
	ds_read_b128 v[198:201], v240 offset:19456
	s_addc_u32 s45, s1, s31
	s_add_u32 s44, s44, 0x100
	s_addc_u32 s45, s45, 0
	s_add_u32 s72, s65, s30
	s_addc_u32 s73, s66, s31
	s_cmpk_eq_i32 s30, 0x700
	s_cselect_b32 s47, s29, s45
	s_cselect_b32 s46, s62, s44
	s_cselect_b32 s45, s63, s73
	s_cselect_b32 s44, s64, s72
	s_add_u32 s90, s0, s30
	s_addc_u32 s91, s1, s31
	s_add_i32 m0, s43, 0xc000
	ds_read_b128 v[202:205], v176
	ds_read_b128 v[206:209], v176 offset:1024
	ds_read_b128 v[210:213], v176 offset:2048
	ds_read_b128 v[214:217], v176 offset:3072
	ds_read_b128 v[218:221], v176 offset:4096
	ds_read_b128 v[222:225], v176 offset:5120
	ds_read_b128 v[226:229], v176 offset:6144
	ds_read_b128 v[230:233], v176 offset:7168
	global_load_lds_dwordx4 v148, s[90:91]
	s_add_i32 m0, s43, 0xe000
	s_nop 0
	global_load_lds_dwordx4 v150, s[90:91]
	s_waitcnt vmcnt(8)
	s_waitcnt lgkmcnt(0)
	s_barrier
	s_setprio 1
	v_mfma_f32_16x16x32_bf16 v[126:129], v[160:163], v[202:205], 0
	v_mfma_f32_16x16x32_bf16 v[126:129], v[164:167], v[206:209], v[126:129]
	v_mfma_f32_16x16x32_bf16 v[122:125], v[178:181], v[202:205], 0
	v_mfma_f32_16x16x32_bf16 v[122:125], v[182:185], v[206:209], v[122:125]
	v_mfma_f32_16x16x32_bf16 v[110:113], v[160:163], v[210:213], 0
	v_mfma_f32_16x16x32_bf16 v[110:113], v[164:167], v[214:217], v[110:113]
	v_mfma_f32_16x16x32_bf16 v[106:109], v[178:181], v[210:213], 0
	v_mfma_f32_16x16x32_bf16 v[106:109], v[182:185], v[214:217], v[106:109]
	v_mfma_f32_16x16x32_bf16 v[94:97], v[160:163], v[218:221], 0
	v_mfma_f32_16x16x32_bf16 v[94:97], v[164:167], v[222:225], v[94:97]
	v_mfma_f32_16x16x32_bf16 v[90:93], v[178:181], v[218:221], 0
	v_mfma_f32_16x16x32_bf16 v[90:93], v[182:185], v[222:225], v[90:93]
	v_mfma_f32_16x16x32_bf16 v[78:81], v[160:163], v[226:229], 0
	v_mfma_f32_16x16x32_bf16 v[78:81], v[164:167], v[230:233], v[78:81]
	v_mfma_f32_16x16x32_bf16 v[74:77], v[178:181], v[226:229], 0
	v_mfma_f32_16x16x32_bf16 v[74:77], v[182:185], v[230:233], v[74:77]
	v_mfma_f32_16x16x32_bf16 v[118:121], v[186:189], v[202:205], 0
	v_mfma_f32_16x16x32_bf16 v[118:121], v[190:193], v[206:209], v[118:121]
	v_mfma_f32_16x16x32_bf16 v[114:117], v[194:197], v[202:205], 0
	v_mfma_f32_16x16x32_bf16 v[114:117], v[198:201], v[206:209], v[114:117]
	v_mfma_f32_16x16x32_bf16 v[102:105], v[186:189], v[210:213], 0
	v_mfma_f32_16x16x32_bf16 v[102:105], v[190:193], v[214:217], v[102:105]
	v_mfma_f32_16x16x32_bf16 v[98:101], v[194:197], v[210:213], 0
	v_mfma_f32_16x16x32_bf16 v[98:101], v[198:201], v[214:217], v[98:101]
	v_mfma_f32_16x16x32_bf16 v[86:89], v[186:189], v[218:221], 0
	v_mfma_f32_16x16x32_bf16 v[86:89], v[190:193], v[222:225], v[86:89]
	v_mfma_f32_16x16x32_bf16 v[82:85], v[194:197], v[218:221], 0
	v_mfma_f32_16x16x32_bf16 v[82:85], v[198:201], v[222:225], v[82:85]
	s_setprio 2
	s_barrier
	v_mfma_f32_16x16x32_bf16 v[70:73], v[186:189], v[226:229], 0
	v_mfma_f32_16x16x32_bf16 v[70:73], v[190:193], v[230:233], v[70:73]
	v_mfma_f32_16x16x32_bf16 v[66:69], v[194:197], v[226:229], 0
	v_mfma_f32_16x16x32_bf16 v[66:69], v[198:201], v[230:233], v[66:69]
	s_setprio 0
	s_nop 0
	s_add_i32 s72, s60, s33
	s_mov_b32 m0, s72
	ds_read_b128 v[202:205], v176 offset:16384
	ds_read_b128 v[206:209], v176 offset:17408
	ds_read_b128 v[210:213], v176 offset:18432
	ds_read_b128 v[214:217], v176 offset:19456
	ds_read_b128 v[218:221], v176 offset:20480
	ds_read_b128 v[222:225], v176 offset:21504
	ds_read_b128 v[226:229], v176 offset:22528
	ds_read_b128 v[230:233], v176 offset:23552
	global_load_lds_dwordx4 v140, s[44:45]
	s_add_i32 m0, s72, 0x2000
	s_add_u32 s72, s44, 0x40000
	s_addc_u32 s73, s45, 0
	s_add_i32 s74, s61, s33
	global_load_lds_dwordx4 v144, s[44:45]
	s_mov_b32 m0, s74
	s_add_u32 s94, s46, 0x80
	s_addc_u32 s95, s47, 0
	global_load_lds_dwordx4 v140, s[72:73]
	s_add_i32 m0, s74, 0x2000
	s_nop 0
	global_load_lds_dwordx4 v144, s[72:73]
	s_mov_b32 m0, s43
	s_nop 0
	global_load_lds_dwordx4 v138, s[46:47]
	s_mov_b32 m0, s54
	s_nop 0
	global_load_lds_dwordx4 v142, s[46:47]
	s_waitcnt vmcnt(8)
	s_waitcnt lgkmcnt(0)
	s_barrier
	s_setprio 1
	v_mfma_f32_16x16x32_bf16 v[62:65], v[160:163], v[202:205], 0
	v_mfma_f32_16x16x32_bf16 v[62:65], v[164:167], v[206:209], v[62:65]
	v_mfma_f32_16x16x32_bf16 v[58:61], v[178:181], v[202:205], 0
	v_mfma_f32_16x16x32_bf16 v[58:61], v[182:185], v[206:209], v[58:61]
	v_mfma_f32_16x16x32_bf16 v[46:49], v[160:163], v[210:213], 0
	v_mfma_f32_16x16x32_bf16 v[46:49], v[164:167], v[214:217], v[46:49]
	v_mfma_f32_16x16x32_bf16 v[42:45], v[178:181], v[210:213], 0
	v_mfma_f32_16x16x32_bf16 v[42:45], v[182:185], v[214:217], v[42:45]
	v_mfma_f32_16x16x32_bf16 v[30:33], v[160:163], v[218:221], 0
	v_mfma_f32_16x16x32_bf16 v[30:33], v[164:167], v[222:225], v[30:33]
	v_mfma_f32_16x16x32_bf16 v[26:29], v[178:181], v[218:221], 0
	v_mfma_f32_16x16x32_bf16 v[26:29], v[182:185], v[222:225], v[26:29]
	v_mfma_f32_16x16x32_bf16 v[14:17], v[160:163], v[226:229], 0
	v_mfma_f32_16x16x32_bf16 v[14:17], v[164:167], v[230:233], v[14:17]
	v_mfma_f32_16x16x32_bf16 v[10:13], v[178:181], v[226:229], 0
	v_mfma_f32_16x16x32_bf16 v[10:13], v[182:185], v[230:233], v[10:13]
	v_mfma_f32_16x16x32_bf16 v[54:57], v[186:189], v[202:205], 0
	v_mfma_f32_16x16x32_bf16 v[54:57], v[190:193], v[206:209], v[54:57]
	v_mfma_f32_16x16x32_bf16 v[50:53], v[194:197], v[202:205], 0
	v_mfma_f32_16x16x32_bf16 v[50:53], v[198:201], v[206:209], v[50:53]
	v_mfma_f32_16x16x32_bf16 v[38:41], v[186:189], v[210:213], 0
	v_mfma_f32_16x16x32_bf16 v[38:41], v[190:193], v[214:217], v[38:41]
	v_mfma_f32_16x16x32_bf16 v[34:37], v[194:197], v[210:213], 0
	v_mfma_f32_16x16x32_bf16 v[34:37], v[198:201], v[214:217], v[34:37]
	v_mfma_f32_16x16x32_bf16 v[22:25], v[186:189], v[218:221], 0
	v_mfma_f32_16x16x32_bf16 v[22:25], v[190:193], v[222:225], v[22:25]
	v_mfma_f32_16x16x32_bf16 v[18:21], v[194:197], v[218:221], 0
	v_mfma_f32_16x16x32_bf16 v[18:21], v[198:201], v[222:225], v[18:21]
	s_setprio 2
	s_barrier
	v_mfma_f32_16x16x32_bf16 v[6:9], v[186:189], v[226:229], 0
	v_mfma_f32_16x16x32_bf16 v[6:9], v[190:193], v[230:233], v[6:9]
	v_mfma_f32_16x16x32_bf16 v[2:5], v[194:197], v[226:229], 0
	v_mfma_f32_16x16x32_bf16 v[2:5], v[198:201], v[230:233], v[2:5]
	s_setprio 0
	s_nop 0
	s_add_i32 s72, 0, 0x18000
	s_add_i32 s73, 0, 0x1c000
	ds_read_b128 v[160:163], v240 offset:32768
	ds_read_b128 v[164:167], v240 offset:33792
	ds_read_b128 v[178:181], v240 offset:34816
	ds_read_b128 v[182:185], v240 offset:35840
	ds_read_b128 v[186:189], v240 offset:49152
	ds_read_b128 v[190:193], v240 offset:50176
	ds_read_b128 v[194:197], v240 offset:51200
	ds_read_b128 v[198:201], v240 offset:52224
	s_add_u32 s46, s46, 0x40000
	s_addc_u32 s47, s47, 0
	s_mov_b32 m0, s55
	ds_read_b128 v[202:205], v176 offset:32768
	ds_read_b128 v[206:209], v176 offset:33792
	ds_read_b128 v[210:213], v176 offset:34816
	ds_read_b128 v[214:217], v176 offset:35840
	ds_read_b128 v[218:221], v176 offset:36864
	ds_read_b128 v[222:225], v176 offset:37888
	ds_read_b128 v[226:229], v176 offset:38912
	ds_read_b128 v[230:233], v176 offset:39936
	global_load_lds_dwordx4 v138, s[46:47]
	s_mov_b32 m0, s56
	s_nop 0
	global_load_lds_dwordx4 v142, s[46:47]
	s_waitcnt vmcnt(8)
	s_waitcnt lgkmcnt(0)
	s_barrier
	s_setprio 1
	v_mfma_f32_16x16x32_bf16 v[126:129], v[160:163], v[202:205], v[126:129]
	v_mfma_f32_16x16x32_bf16 v[126:129], v[164:167], v[206:209], v[126:129]
	v_mfma_f32_16x16x32_bf16 v[122:125], v[178:181], v[202:205], v[122:125]
	v_mfma_f32_16x16x32_bf16 v[122:125], v[182:185], v[206:209], v[122:125]
	v_mfma_f32_16x16x32_bf16 v[110:113], v[160:163], v[210:213], v[110:113]
	v_mfma_f32_16x16x32_bf16 v[110:113], v[164:167], v[214:217], v[110:113]
	v_mfma_f32_16x16x32_bf16 v[106:109], v[178:181], v[210:213], v[106:109]
	v_mfma_f32_16x16x32_bf16 v[106:109], v[182:185], v[214:217], v[106:109]
	v_mfma_f32_16x16x32_bf16 v[94:97], v[160:163], v[218:221], v[94:97]
	v_mfma_f32_16x16x32_bf16 v[94:97], v[164:167], v[222:225], v[94:97]
	v_mfma_f32_16x16x32_bf16 v[90:93], v[178:181], v[218:221], v[90:93]
	v_mfma_f32_16x16x32_bf16 v[90:93], v[182:185], v[222:225], v[90:93]
	v_mfma_f32_16x16x32_bf16 v[78:81], v[160:163], v[226:229], v[78:81]
	v_mfma_f32_16x16x32_bf16 v[78:81], v[164:167], v[230:233], v[78:81]
	v_mfma_f32_16x16x32_bf16 v[74:77], v[178:181], v[226:229], v[74:77]
	v_mfma_f32_16x16x32_bf16 v[74:77], v[182:185], v[230:233], v[74:77]
	v_mfma_f32_16x16x32_bf16 v[118:121], v[186:189], v[202:205], v[118:121]
	v_mfma_f32_16x16x32_bf16 v[118:121], v[190:193], v[206:209], v[118:121]
	v_mfma_f32_16x16x32_bf16 v[114:117], v[194:197], v[202:205], v[114:117]
	v_mfma_f32_16x16x32_bf16 v[114:117], v[198:201], v[206:209], v[114:117]
	v_mfma_f32_16x16x32_bf16 v[102:105], v[186:189], v[210:213], v[102:105]
	v_mfma_f32_16x16x32_bf16 v[102:105], v[190:193], v[214:217], v[102:105]
	v_mfma_f32_16x16x32_bf16 v[98:101], v[194:197], v[210:213], v[98:101]
	v_mfma_f32_16x16x32_bf16 v[98:101], v[198:201], v[214:217], v[98:101]
	v_mfma_f32_16x16x32_bf16 v[86:89], v[186:189], v[218:221], v[86:89]
	v_mfma_f32_16x16x32_bf16 v[86:89], v[190:193], v[222:225], v[86:89]
	v_mfma_f32_16x16x32_bf16 v[82:85], v[194:197], v[218:221], v[82:85]
	v_mfma_f32_16x16x32_bf16 v[82:85], v[198:201], v[222:225], v[82:85]
	s_setprio 2
	s_barrier
	v_mfma_f32_16x16x32_bf16 v[70:73], v[186:189], v[226:229], v[70:73]
	v_mfma_f32_16x16x32_bf16 v[70:73], v[190:193], v[230:233], v[70:73]
	v_mfma_f32_16x16x32_bf16 v[66:69], v[194:197], v[226:229], v[66:69]
	v_mfma_f32_16x16x32_bf16 v[66:69], v[198:201], v[230:233], v[66:69]
	s_setprio 0
	s_nop 0
	s_add_i32 s46, s72, s33
	s_add_u32 s96, s44, 0x80
	s_addc_u32 s97, s45, 0
	s_mov_b32 m0, s46
	ds_read_b128 v[202:205], v176 offset:49152
	ds_read_b128 v[206:209], v176 offset:50176
	ds_read_b128 v[210:213], v176 offset:51200
	ds_read_b128 v[214:217], v176 offset:52224
	ds_read_b128 v[218:221], v176 offset:53248
	ds_read_b128 v[222:225], v176 offset:54272
	ds_read_b128 v[226:229], v176 offset:55296
	ds_read_b128 v[230:233], v176 offset:56320
	global_load_lds_dwordx4 v140, s[96:97]
	s_add_i32 m0, s46, 0x2000
	s_add_u32 s44, s44, 0x40080
	s_addc_u32 s45, s45, 0
	s_add_i32 s46, s73, s33
	global_load_lds_dwordx4 v144, s[96:97]
	s_mov_b32 m0, s46
	s_nop 0
	global_load_lds_dwordx4 v140, s[44:45]
	s_add_i32 m0, s46, 0x2000
	s_nop 0
	global_load_lds_dwordx4 v144, s[44:45]
	s_mov_b32 m0, s57
	s_nop 0
	global_load_lds_dwordx4 v138, s[94:95]
	s_mov_b32 m0, s58
	s_nop 0
	global_load_lds_dwordx4 v142, s[94:95]
	s_waitcnt vmcnt(8)
	s_waitcnt lgkmcnt(0)
	s_barrier
	s_setprio 1
	v_mfma_f32_16x16x32_bf16 v[62:65], v[160:163], v[202:205], v[62:65]
	v_mfma_f32_16x16x32_bf16 v[62:65], v[164:167], v[206:209], v[62:65]
	v_mfma_f32_16x16x32_bf16 v[58:61], v[178:181], v[202:205], v[58:61]
	v_mfma_f32_16x16x32_bf16 v[58:61], v[182:185], v[206:209], v[58:61]
	v_mfma_f32_16x16x32_bf16 v[46:49], v[160:163], v[210:213], v[46:49]
	v_mfma_f32_16x16x32_bf16 v[46:49], v[164:167], v[214:217], v[46:49]
	v_mfma_f32_16x16x32_bf16 v[42:45], v[178:181], v[210:213], v[42:45]
	v_mfma_f32_16x16x32_bf16 v[42:45], v[182:185], v[214:217], v[42:45]
	v_mfma_f32_16x16x32_bf16 v[30:33], v[160:163], v[218:221], v[30:33]
	v_mfma_f32_16x16x32_bf16 v[30:33], v[164:167], v[222:225], v[30:33]
	v_mfma_f32_16x16x32_bf16 v[26:29], v[178:181], v[218:221], v[26:29]
	v_mfma_f32_16x16x32_bf16 v[26:29], v[182:185], v[222:225], v[26:29]
	v_mfma_f32_16x16x32_bf16 v[14:17], v[160:163], v[226:229], v[14:17]
	v_mfma_f32_16x16x32_bf16 v[14:17], v[164:167], v[230:233], v[14:17]
	v_mfma_f32_16x16x32_bf16 v[10:13], v[178:181], v[226:229], v[10:13]
	v_mfma_f32_16x16x32_bf16 v[10:13], v[182:185], v[230:233], v[10:13]
	v_mfma_f32_16x16x32_bf16 v[54:57], v[186:189], v[202:205], v[54:57]
	v_mfma_f32_16x16x32_bf16 v[54:57], v[190:193], v[206:209], v[54:57]
	v_mfma_f32_16x16x32_bf16 v[50:53], v[194:197], v[202:205], v[50:53]
	v_mfma_f32_16x16x32_bf16 v[50:53], v[198:201], v[206:209], v[50:53]
	v_mfma_f32_16x16x32_bf16 v[38:41], v[186:189], v[210:213], v[38:41]
	v_mfma_f32_16x16x32_bf16 v[38:41], v[190:193], v[214:217], v[38:41]
	v_mfma_f32_16x16x32_bf16 v[34:37], v[194:197], v[210:213], v[34:37]
	v_mfma_f32_16x16x32_bf16 v[34:37], v[198:201], v[214:217], v[34:37]
	v_mfma_f32_16x16x32_bf16 v[22:25], v[186:189], v[218:221], v[22:25]
	v_mfma_f32_16x16x32_bf16 v[22:25], v[190:193], v[222:225], v[22:25]
	v_mfma_f32_16x16x32_bf16 v[18:21], v[194:197], v[218:221], v[18:21]
	v_mfma_f32_16x16x32_bf16 v[18:21], v[198:201], v[222:225], v[18:21]
	s_setprio 2
	s_barrier
	v_mfma_f32_16x16x32_bf16 v[6:9], v[186:189], v[226:229], v[6:9]
	v_mfma_f32_16x16x32_bf16 v[6:9], v[190:193], v[230:233], v[6:9]
	v_mfma_f32_16x16x32_bf16 v[2:5], v[194:197], v[226:229], v[2:5]
	v_mfma_f32_16x16x32_bf16 v[2:5], v[198:201], v[230:233], v[2:5]
	s_setprio 0
	s_nop 0
	s_add_i32 s67, s67, 2
	s_add_u32 s30, s30, 0x100
	s_addc_u32 s31, s31, 0
	s_cmp_gt_u32 s67, 13
	s_cbranch_scc1 .LBB0_181
	s_branch .LBB0_179
.LBB0_178:
	s_waitcnt lgkmcnt(0)
	ds_read_b128 v[160:163], v240
	ds_read_b128 v[164:167], v240 offset:1024
	ds_read_b128 v[178:181], v240 offset:2048
	ds_read_b128 v[182:185], v240 offset:3072
	s_add_u32 s44, s0, s30
	ds_read_b128 v[186:189], v240 offset:16384
	ds_read_b128 v[190:193], v240 offset:17408
	ds_read_b128 v[194:197], v240 offset:18432
	ds_read_b128 v[198:201], v240 offset:19456
	s_addc_u32 s45, s1, s31
	s_add_u32 s44, s44, 0x100
	s_addc_u32 s45, s45, 0
	s_add_u32 s72, s65, s30
	s_addc_u32 s73, s66, s31
	s_cmpk_eq_i32 s30, 0x700
	s_cselect_b32 s47, s29, s45
	s_cselect_b32 s46, s62, s44
	s_cselect_b32 s45, s63, s73
	s_cselect_b32 s44, s64, s72
	s_add_u32 s90, s0, s30
	s_addc_u32 s91, s1, s31
	s_add_i32 m0, s43, 0xc000
	ds_read_b128 v[202:205], v176
	ds_read_b128 v[206:209], v176 offset:1024
	ds_read_b128 v[210:213], v176 offset:2048
	ds_read_b128 v[214:217], v176 offset:3072
	ds_read_b128 v[218:221], v176 offset:4096
	ds_read_b128 v[222:225], v176 offset:5120
	ds_read_b128 v[226:229], v176 offset:6144
	ds_read_b128 v[230:233], v176 offset:7168
	global_load_lds_dwordx4 v148, s[90:91]
	s_add_i32 m0, s43, 0xe000
	s_nop 0
	global_load_lds_dwordx4 v150, s[90:91]
	s_waitcnt vmcnt(8)
	s_waitcnt lgkmcnt(0)
	s_barrier
	s_setprio 1
	v_mfma_f32_16x16x32_bf16 v[126:129], v[160:163], v[202:205], v[126:129]
	v_mfma_f32_16x16x32_bf16 v[126:129], v[164:167], v[206:209], v[126:129]
	v_mfma_f32_16x16x32_bf16 v[122:125], v[178:181], v[202:205], v[122:125]
	v_mfma_f32_16x16x32_bf16 v[122:125], v[182:185], v[206:209], v[122:125]
	v_mfma_f32_16x16x32_bf16 v[110:113], v[160:163], v[210:213], v[110:113]
	v_mfma_f32_16x16x32_bf16 v[110:113], v[164:167], v[214:217], v[110:113]
	v_mfma_f32_16x16x32_bf16 v[106:109], v[178:181], v[210:213], v[106:109]
	v_mfma_f32_16x16x32_bf16 v[106:109], v[182:185], v[214:217], v[106:109]
	v_mfma_f32_16x16x32_bf16 v[94:97], v[160:163], v[218:221], v[94:97]
	v_mfma_f32_16x16x32_bf16 v[94:97], v[164:167], v[222:225], v[94:97]
	v_mfma_f32_16x16x32_bf16 v[90:93], v[178:181], v[218:221], v[90:93]
	v_mfma_f32_16x16x32_bf16 v[90:93], v[182:185], v[222:225], v[90:93]
	v_mfma_f32_16x16x32_bf16 v[78:81], v[160:163], v[226:229], v[78:81]
	v_mfma_f32_16x16x32_bf16 v[78:81], v[164:167], v[230:233], v[78:81]
	v_mfma_f32_16x16x32_bf16 v[74:77], v[178:181], v[226:229], v[74:77]
	v_mfma_f32_16x16x32_bf16 v[74:77], v[182:185], v[230:233], v[74:77]
	v_mfma_f32_16x16x32_bf16 v[118:121], v[186:189], v[202:205], v[118:121]
	v_mfma_f32_16x16x32_bf16 v[118:121], v[190:193], v[206:209], v[118:121]
	v_mfma_f32_16x16x32_bf16 v[114:117], v[194:197], v[202:205], v[114:117]
	v_mfma_f32_16x16x32_bf16 v[114:117], v[198:201], v[206:209], v[114:117]
	v_mfma_f32_16x16x32_bf16 v[102:105], v[186:189], v[210:213], v[102:105]
	v_mfma_f32_16x16x32_bf16 v[102:105], v[190:193], v[214:217], v[102:105]
	v_mfma_f32_16x16x32_bf16 v[98:101], v[194:197], v[210:213], v[98:101]
	v_mfma_f32_16x16x32_bf16 v[98:101], v[198:201], v[214:217], v[98:101]
	v_mfma_f32_16x16x32_bf16 v[86:89], v[186:189], v[218:221], v[86:89]
	v_mfma_f32_16x16x32_bf16 v[86:89], v[190:193], v[222:225], v[86:89]
	v_mfma_f32_16x16x32_bf16 v[82:85], v[194:197], v[218:221], v[82:85]
	v_mfma_f32_16x16x32_bf16 v[82:85], v[198:201], v[222:225], v[82:85]
	s_setprio 2
	s_barrier
	v_mfma_f32_16x16x32_bf16 v[70:73], v[186:189], v[226:229], v[70:73]
	v_mfma_f32_16x16x32_bf16 v[70:73], v[190:193], v[230:233], v[70:73]
	v_mfma_f32_16x16x32_bf16 v[66:69], v[194:197], v[226:229], v[66:69]
	v_mfma_f32_16x16x32_bf16 v[66:69], v[198:201], v[230:233], v[66:69]
	s_setprio 0
	s_nop 0
	s_add_i32 s72, s60, s33
	s_mov_b32 m0, s72
	ds_read_b128 v[202:205], v176 offset:16384
	ds_read_b128 v[206:209], v176 offset:17408
	ds_read_b128 v[210:213], v176 offset:18432
	ds_read_b128 v[214:217], v176 offset:19456
	ds_read_b128 v[218:221], v176 offset:20480
	ds_read_b128 v[222:225], v176 offset:21504
	ds_read_b128 v[226:229], v176 offset:22528
	ds_read_b128 v[230:233], v176 offset:23552
	global_load_lds_dwordx4 v140, s[44:45]
	s_add_i32 m0, s72, 0x2000
	s_add_u32 s72, s44, 0x40000
	s_addc_u32 s73, s45, 0
	s_add_i32 s74, s61, s33
	global_load_lds_dwordx4 v144, s[44:45]
	s_mov_b32 m0, s74
	s_add_u32 s94, s46, 0x80
	s_addc_u32 s95, s47, 0
	global_load_lds_dwordx4 v140, s[72:73]
	s_add_i32 m0, s74, 0x2000
	s_nop 0
	global_load_lds_dwordx4 v144, s[72:73]
	s_mov_b32 m0, s43
	s_nop 0
	global_load_lds_dwordx4 v138, s[46:47]
	s_mov_b32 m0, s54
	s_nop 0
	global_load_lds_dwordx4 v142, s[46:47]
	s_waitcnt vmcnt(8)
	s_waitcnt lgkmcnt(0)
	s_barrier
	s_setprio 1
	v_mfma_f32_16x16x32_bf16 v[62:65], v[160:163], v[202:205], v[62:65]
	v_mfma_f32_16x16x32_bf16 v[62:65], v[164:167], v[206:209], v[62:65]
	v_mfma_f32_16x16x32_bf16 v[58:61], v[178:181], v[202:205], v[58:61]
	v_mfma_f32_16x16x32_bf16 v[58:61], v[182:185], v[206:209], v[58:61]
	v_mfma_f32_16x16x32_bf16 v[46:49], v[160:163], v[210:213], v[46:49]
	v_mfma_f32_16x16x32_bf16 v[46:49], v[164:167], v[214:217], v[46:49]
	v_mfma_f32_16x16x32_bf16 v[42:45], v[178:181], v[210:213], v[42:45]
	v_mfma_f32_16x16x32_bf16 v[42:45], v[182:185], v[214:217], v[42:45]
	v_mfma_f32_16x16x32_bf16 v[30:33], v[160:163], v[218:221], v[30:33]
	v_mfma_f32_16x16x32_bf16 v[30:33], v[164:167], v[222:225], v[30:33]
	v_mfma_f32_16x16x32_bf16 v[26:29], v[178:181], v[218:221], v[26:29]
	v_mfma_f32_16x16x32_bf16 v[26:29], v[182:185], v[222:225], v[26:29]
	v_mfma_f32_16x16x32_bf16 v[14:17], v[160:163], v[226:229], v[14:17]
	v_mfma_f32_16x16x32_bf16 v[14:17], v[164:167], v[230:233], v[14:17]
	v_mfma_f32_16x16x32_bf16 v[10:13], v[178:181], v[226:229], v[10:13]
	v_mfma_f32_16x16x32_bf16 v[10:13], v[182:185], v[230:233], v[10:13]
	v_mfma_f32_16x16x32_bf16 v[54:57], v[186:189], v[202:205], v[54:57]
	v_mfma_f32_16x16x32_bf16 v[54:57], v[190:193], v[206:209], v[54:57]
	v_mfma_f32_16x16x32_bf16 v[50:53], v[194:197], v[202:205], v[50:53]
	v_mfma_f32_16x16x32_bf16 v[50:53], v[198:201], v[206:209], v[50:53]
	v_mfma_f32_16x16x32_bf16 v[38:41], v[186:189], v[210:213], v[38:41]
	v_mfma_f32_16x16x32_bf16 v[38:41], v[190:193], v[214:217], v[38:41]
	v_mfma_f32_16x16x32_bf16 v[34:37], v[194:197], v[210:213], v[34:37]
	v_mfma_f32_16x16x32_bf16 v[34:37], v[198:201], v[214:217], v[34:37]
	v_mfma_f32_16x16x32_bf16 v[22:25], v[186:189], v[218:221], v[22:25]
	v_mfma_f32_16x16x32_bf16 v[22:25], v[190:193], v[222:225], v[22:25]
	v_mfma_f32_16x16x32_bf16 v[18:21], v[194:197], v[218:221], v[18:21]
	v_mfma_f32_16x16x32_bf16 v[18:21], v[198:201], v[222:225], v[18:21]
	s_setprio 2
	s_barrier
	v_mfma_f32_16x16x32_bf16 v[6:9], v[186:189], v[226:229], v[6:9]
	v_mfma_f32_16x16x32_bf16 v[6:9], v[190:193], v[230:233], v[6:9]
	v_mfma_f32_16x16x32_bf16 v[2:5], v[194:197], v[226:229], v[2:5]
	v_mfma_f32_16x16x32_bf16 v[2:5], v[198:201], v[230:233], v[2:5]
	s_setprio 0
	s_nop 0
	s_add_i32 s72, 0, 0x18000
	s_add_i32 s73, 0, 0x1c000
	ds_read_b128 v[160:163], v240 offset:32768
	ds_read_b128 v[164:167], v240 offset:33792
	ds_read_b128 v[178:181], v240 offset:34816
	ds_read_b128 v[182:185], v240 offset:35840
	ds_read_b128 v[186:189], v240 offset:49152
	ds_read_b128 v[190:193], v240 offset:50176
	ds_read_b128 v[194:197], v240 offset:51200
	ds_read_b128 v[198:201], v240 offset:52224
	s_add_u32 s46, s46, 0x40000
	s_addc_u32 s47, s47, 0
	s_mov_b32 m0, s55
	ds_read_b128 v[202:205], v176 offset:32768
	ds_read_b128 v[206:209], v176 offset:33792
	ds_read_b128 v[210:213], v176 offset:34816
	ds_read_b128 v[214:217], v176 offset:35840
	ds_read_b128 v[218:221], v176 offset:36864
	ds_read_b128 v[222:225], v176 offset:37888
	ds_read_b128 v[226:229], v176 offset:38912
	ds_read_b128 v[230:233], v176 offset:39936
	global_load_lds_dwordx4 v138, s[46:47]
	s_mov_b32 m0, s56
	s_nop 0
	global_load_lds_dwordx4 v142, s[46:47]
	s_waitcnt vmcnt(8)
	s_waitcnt lgkmcnt(0)
	s_barrier
	s_setprio 1
	v_mfma_f32_16x16x32_bf16 v[126:129], v[160:163], v[202:205], v[126:129]
	v_mfma_f32_16x16x32_bf16 v[126:129], v[164:167], v[206:209], v[126:129]
	v_mfma_f32_16x16x32_bf16 v[122:125], v[178:181], v[202:205], v[122:125]
	v_mfma_f32_16x16x32_bf16 v[122:125], v[182:185], v[206:209], v[122:125]
	v_mfma_f32_16x16x32_bf16 v[110:113], v[160:163], v[210:213], v[110:113]
	v_mfma_f32_16x16x32_bf16 v[110:113], v[164:167], v[214:217], v[110:113]
	v_mfma_f32_16x16x32_bf16 v[106:109], v[178:181], v[210:213], v[106:109]
	v_mfma_f32_16x16x32_bf16 v[106:109], v[182:185], v[214:217], v[106:109]
	v_mfma_f32_16x16x32_bf16 v[94:97], v[160:163], v[218:221], v[94:97]
	v_mfma_f32_16x16x32_bf16 v[94:97], v[164:167], v[222:225], v[94:97]
	v_mfma_f32_16x16x32_bf16 v[90:93], v[178:181], v[218:221], v[90:93]
	v_mfma_f32_16x16x32_bf16 v[90:93], v[182:185], v[222:225], v[90:93]
	v_mfma_f32_16x16x32_bf16 v[78:81], v[160:163], v[226:229], v[78:81]
	v_mfma_f32_16x16x32_bf16 v[78:81], v[164:167], v[230:233], v[78:81]
	v_mfma_f32_16x16x32_bf16 v[74:77], v[178:181], v[226:229], v[74:77]
	v_mfma_f32_16x16x32_bf16 v[74:77], v[182:185], v[230:233], v[74:77]
	v_mfma_f32_16x16x32_bf16 v[118:121], v[186:189], v[202:205], v[118:121]
	v_mfma_f32_16x16x32_bf16 v[118:121], v[190:193], v[206:209], v[118:121]
	v_mfma_f32_16x16x32_bf16 v[114:117], v[194:197], v[202:205], v[114:117]
	v_mfma_f32_16x16x32_bf16 v[114:117], v[198:201], v[206:209], v[114:117]
	v_mfma_f32_16x16x32_bf16 v[102:105], v[186:189], v[210:213], v[102:105]
	v_mfma_f32_16x16x32_bf16 v[102:105], v[190:193], v[214:217], v[102:105]
	v_mfma_f32_16x16x32_bf16 v[98:101], v[194:197], v[210:213], v[98:101]
	v_mfma_f32_16x16x32_bf16 v[98:101], v[198:201], v[214:217], v[98:101]
	v_mfma_f32_16x16x32_bf16 v[86:89], v[186:189], v[218:221], v[86:89]
	v_mfma_f32_16x16x32_bf16 v[86:89], v[190:193], v[222:225], v[86:89]
	v_mfma_f32_16x16x32_bf16 v[82:85], v[194:197], v[218:221], v[82:85]
	v_mfma_f32_16x16x32_bf16 v[82:85], v[198:201], v[222:225], v[82:85]
	s_setprio 2
	s_barrier
	v_mfma_f32_16x16x32_bf16 v[70:73], v[186:189], v[226:229], v[70:73]
	v_mfma_f32_16x16x32_bf16 v[70:73], v[190:193], v[230:233], v[70:73]
	v_mfma_f32_16x16x32_bf16 v[66:69], v[194:197], v[226:229], v[66:69]
	v_mfma_f32_16x16x32_bf16 v[66:69], v[198:201], v[230:233], v[66:69]
	s_setprio 0
	s_nop 0
	s_add_i32 s46, s72, s33
	s_add_u32 s96, s44, 0x80
	s_addc_u32 s97, s45, 0
	s_mov_b32 m0, s46
	ds_read_b128 v[202:205], v176 offset:49152
	ds_read_b128 v[206:209], v176 offset:50176
	ds_read_b128 v[210:213], v176 offset:51200
	ds_read_b128 v[214:217], v176 offset:52224
	ds_read_b128 v[218:221], v176 offset:53248
	ds_read_b128 v[222:225], v176 offset:54272
	ds_read_b128 v[226:229], v176 offset:55296
	ds_read_b128 v[230:233], v176 offset:56320
	global_load_lds_dwordx4 v140, s[96:97]
	s_add_i32 m0, s46, 0x2000
	s_add_u32 s44, s44, 0x40080
	s_addc_u32 s45, s45, 0
	s_add_i32 s46, s73, s33
	global_load_lds_dwordx4 v144, s[96:97]
	s_mov_b32 m0, s46
	s_nop 0
	global_load_lds_dwordx4 v140, s[44:45]
	s_add_i32 m0, s46, 0x2000
	s_nop 0
	global_load_lds_dwordx4 v144, s[44:45]
	s_mov_b32 m0, s57
	s_nop 0
	global_load_lds_dwordx4 v138, s[94:95]
	s_mov_b32 m0, s58
	s_nop 0
	global_load_lds_dwordx4 v142, s[94:95]
	s_waitcnt vmcnt(8)
	s_waitcnt lgkmcnt(0)
	s_barrier
	s_setprio 1
	v_mfma_f32_16x16x32_bf16 v[62:65], v[160:163], v[202:205], v[62:65]
	v_mfma_f32_16x16x32_bf16 v[62:65], v[164:167], v[206:209], v[62:65]
	v_mfma_f32_16x16x32_bf16 v[58:61], v[178:181], v[202:205], v[58:61]
	v_mfma_f32_16x16x32_bf16 v[58:61], v[182:185], v[206:209], v[58:61]
	v_mfma_f32_16x16x32_bf16 v[46:49], v[160:163], v[210:213], v[46:49]
	v_mfma_f32_16x16x32_bf16 v[46:49], v[164:167], v[214:217], v[46:49]
	v_mfma_f32_16x16x32_bf16 v[42:45], v[178:181], v[210:213], v[42:45]
	v_mfma_f32_16x16x32_bf16 v[42:45], v[182:185], v[214:217], v[42:45]
	v_mfma_f32_16x16x32_bf16 v[30:33], v[160:163], v[218:221], v[30:33]
	v_mfma_f32_16x16x32_bf16 v[30:33], v[164:167], v[222:225], v[30:33]
	v_mfma_f32_16x16x32_bf16 v[26:29], v[178:181], v[218:221], v[26:29]
	v_mfma_f32_16x16x32_bf16 v[26:29], v[182:185], v[222:225], v[26:29]
	v_mfma_f32_16x16x32_bf16 v[14:17], v[160:163], v[226:229], v[14:17]
	v_mfma_f32_16x16x32_bf16 v[14:17], v[164:167], v[230:233], v[14:17]
	v_mfma_f32_16x16x32_bf16 v[10:13], v[178:181], v[226:229], v[10:13]
	v_mfma_f32_16x16x32_bf16 v[10:13], v[182:185], v[230:233], v[10:13]
	v_mfma_f32_16x16x32_bf16 v[54:57], v[186:189], v[202:205], v[54:57]
	v_mfma_f32_16x16x32_bf16 v[54:57], v[190:193], v[206:209], v[54:57]
	v_mfma_f32_16x16x32_bf16 v[50:53], v[194:197], v[202:205], v[50:53]
	v_mfma_f32_16x16x32_bf16 v[50:53], v[198:201], v[206:209], v[50:53]
	v_mfma_f32_16x16x32_bf16 v[38:41], v[186:189], v[210:213], v[38:41]
	v_mfma_f32_16x16x32_bf16 v[38:41], v[190:193], v[214:217], v[38:41]
	v_mfma_f32_16x16x32_bf16 v[34:37], v[194:197], v[210:213], v[34:37]
	v_mfma_f32_16x16x32_bf16 v[34:37], v[198:201], v[214:217], v[34:37]
	v_mfma_f32_16x16x32_bf16 v[22:25], v[186:189], v[218:221], v[22:25]
	v_mfma_f32_16x16x32_bf16 v[22:25], v[190:193], v[222:225], v[22:25]
	v_mfma_f32_16x16x32_bf16 v[18:21], v[194:197], v[218:221], v[18:21]
	v_mfma_f32_16x16x32_bf16 v[18:21], v[198:201], v[222:225], v[18:21]
	s_setprio 2
	s_barrier
	v_mfma_f32_16x16x32_bf16 v[6:9], v[186:189], v[226:229], v[6:9]
	v_mfma_f32_16x16x32_bf16 v[6:9], v[190:193], v[230:233], v[6:9]
	v_mfma_f32_16x16x32_bf16 v[2:5], v[194:197], v[226:229], v[2:5]
	v_mfma_f32_16x16x32_bf16 v[2:5], v[198:201], v[230:233], v[2:5]
	s_setprio 0
	s_nop 0
	s_add_i32 s67, s67, 2
	s_add_u32 s30, s30, 0x100
	s_addc_u32 s31, s31, 0
	s_cmp_gt_u32 s67, 13
	s_cbranch_scc1 .LBB0_181

.LBB0_587:
	s_add_u32 s4, s36, s38
	s_addc_u32 s5, s37, s39
	s_add_u32 s4, s4, 0x100
	s_addc_u32 s5, s5, 0
	s_add_u32 s72, s65, s38
	s_addc_u32 s73, s66, s39
	s_add_i32 s74, 0, 0x10000
	v_add_u32_e32 v3, s74, v213
	ds_read_b128 v[134:137], v3
	ds_read_b128 v[138:141], v3 offset:1024
	ds_read_b128 v[142:145], v3 offset:2048
	ds_read_b128 v[146:149], v3 offset:3072
	v_add_u32_e32 v3, s63, v213
	ds_read_b128 v[150:153], v3
	ds_read_b128 v[154:157], v3 offset:1024
	ds_read_b128 v[158:161], v3 offset:2048
	ds_read_b128 v[162:165], v3 offset:3072
	s_cmpk_eq_i32 s38, 0x700
	s_cselect_b32 s41, s3, s5
	s_cselect_b32 s40, s23, s4
	s_cselect_b32 s5, s25, s73
	s_cselect_b32 s4, s64, s72
	v_lshl_add_u64 v[4:5], v[170:171], 0, s[38:39]
	s_add_i32 m0, s31, 0xc000
	ds_read_b128 v[166:169], v217
	ds_read_b128 v[176:179], v217 offset:1024
	ds_read_b128 v[180:183], v217 offset:2048
	ds_read_b128 v[184:187], v217 offset:3072
	ds_read_b128 v[188:191], v217 offset:4096
	ds_read_b128 v[192:195], v217 offset:5120
	ds_read_b128 v[218:221], v217 offset:6144
	ds_read_b128 v[222:225], v217 offset:7168
	global_load_lds_dwordx4 v[4:5], off
	v_lshl_add_u64 v[4:5], v[172:173], 0, s[38:39]
	s_add_i32 m0, s31, 0xe000
	s_nop 0
	global_load_lds_dwordx4 v[4:5], off
	s_waitcnt vmcnt(8)
	s_waitcnt lgkmcnt(0)
	s_barrier
	s_setprio 1
	v_mfma_f32_16x16x32_bf16 v[130:133], v[134:137], v[166:169], v[130:133]
	v_mfma_f32_16x16x32_bf16 v[130:133], v[138:141], v[176:179], v[130:133]
	v_mfma_f32_16x16x32_bf16 v[126:129], v[142:145], v[166:169], v[126:129]
	v_mfma_f32_16x16x32_bf16 v[126:129], v[146:149], v[176:179], v[126:129]
	v_mfma_f32_16x16x32_bf16 v[114:117], v[134:137], v[180:183], v[114:117]
	v_mfma_f32_16x16x32_bf16 v[114:117], v[138:141], v[184:187], v[114:117]
	v_mfma_f32_16x16x32_bf16 v[110:113], v[142:145], v[180:183], v[110:113]
	v_mfma_f32_16x16x32_bf16 v[110:113], v[146:149], v[184:187], v[110:113]
	v_mfma_f32_16x16x32_bf16 v[98:101], v[134:137], v[188:191], v[98:101]
	v_mfma_f32_16x16x32_bf16 v[98:101], v[138:141], v[192:195], v[98:101]
	v_mfma_f32_16x16x32_bf16 v[94:97], v[142:145], v[188:191], v[94:97]
	v_mfma_f32_16x16x32_bf16 v[94:97], v[146:149], v[192:195], v[94:97]
	v_mfma_f32_16x16x32_bf16 v[82:85], v[134:137], v[218:221], v[82:85]
	v_mfma_f32_16x16x32_bf16 v[82:85], v[138:141], v[222:225], v[82:85]
	v_mfma_f32_16x16x32_bf16 v[78:81], v[142:145], v[218:221], v[78:81]
	v_mfma_f32_16x16x32_bf16 v[78:81], v[146:149], v[222:225], v[78:81]
	v_mfma_f32_16x16x32_bf16 v[122:125], v[150:153], v[166:169], v[122:125]
	v_mfma_f32_16x16x32_bf16 v[122:125], v[154:157], v[176:179], v[122:125]
	v_mfma_f32_16x16x32_bf16 v[118:121], v[158:161], v[166:169], v[118:121]
	v_mfma_f32_16x16x32_bf16 v[118:121], v[162:165], v[176:179], v[118:121]
	v_mfma_f32_16x16x32_bf16 v[106:109], v[150:153], v[180:183], v[106:109]
	v_mfma_f32_16x16x32_bf16 v[106:109], v[154:157], v[184:187], v[106:109]
	v_mfma_f32_16x16x32_bf16 v[102:105], v[158:161], v[180:183], v[102:105]
	v_mfma_f32_16x16x32_bf16 v[102:105], v[162:165], v[184:187], v[102:105]
	v_mfma_f32_16x16x32_bf16 v[90:93], v[150:153], v[188:191], v[90:93]
	v_mfma_f32_16x16x32_bf16 v[90:93], v[154:157], v[192:195], v[90:93]
	v_mfma_f32_16x16x32_bf16 v[86:89], v[158:161], v[188:191], v[86:89]
	v_mfma_f32_16x16x32_bf16 v[86:89], v[162:165], v[192:195], v[86:89]
	s_setprio 2
	s_barrier
	v_mfma_f32_16x16x32_bf16 v[74:77], v[150:153], v[218:221], v[74:77]
	v_mfma_f32_16x16x32_bf16 v[74:77], v[154:157], v[222:225], v[74:77]
	v_mfma_f32_16x16x32_bf16 v[70:73], v[158:161], v[218:221], v[70:73]
	v_mfma_f32_16x16x32_bf16 v[70:73], v[162:165], v[222:225], v[70:73]
	s_setprio 0
	s_nop 0
	s_add_i32 s72, s74, s33
	v_lshl_add_u64 v[196:197], s[4:5], 0, v[200:201]
	s_mov_b32 m0, s72
	ds_read_b128 v[166:169], v217 offset:16384
	ds_read_b128 v[176:179], v217 offset:17408
	ds_read_b128 v[180:183], v217 offset:18432
	ds_read_b128 v[184:187], v217 offset:19456
	ds_read_b128 v[188:191], v217 offset:20480
	ds_read_b128 v[192:195], v217 offset:21504
	ds_read_b128 v[218:221], v217 offset:22528
	ds_read_b128 v[222:225], v217 offset:23552
	global_load_lds_dwordx4 v[196:197], off
	s_add_i32 m0, s72, 0x2000
	s_add_u32 s72, s4, 0x40000
	v_lshl_add_u64 v[210:211], s[4:5], 0, v[204:205]
	s_addc_u32 s73, s5, 0
	s_add_i32 s74, s63, s33
	global_load_lds_dwordx4 v[210:211], off
	v_lshl_add_u64 v[4:5], s[72:73], 0, v[200:201]
	s_mov_b32 m0, s74
	v_lshl_add_u64 v[226:227], s[40:41], 0, v[198:199]
	global_load_lds_dwordx4 v[4:5], off
	v_lshl_add_u64 v[4:5], s[72:73], 0, v[204:205]
	s_add_i32 m0, s74, 0x2000
	v_lshl_add_u64 v[230:231], s[40:41], 0, v[202:203]
	global_load_lds_dwordx4 v[4:5], off
	s_mov_b32 m0, s31
	s_nop 0
	global_load_lds_dwordx4 v[226:227], off
	s_mov_b32 m0, s42
	s_nop 0
	global_load_lds_dwordx4 v[230:231], off
	s_waitcnt vmcnt(8)
	s_waitcnt lgkmcnt(0)
	s_barrier
	s_setprio 1
	v_mfma_f32_16x16x32_bf16 v[66:69], v[134:137], v[166:169], v[66:69]
	v_mfma_f32_16x16x32_bf16 v[66:69], v[138:141], v[176:179], v[66:69]
	v_mfma_f32_16x16x32_bf16 v[62:65], v[142:145], v[166:169], v[62:65]
	v_mfma_f32_16x16x32_bf16 v[62:65], v[146:149], v[176:179], v[62:65]
	v_mfma_f32_16x16x32_bf16 v[50:53], v[134:137], v[180:183], v[50:53]
	v_mfma_f32_16x16x32_bf16 v[50:53], v[138:141], v[184:187], v[50:53]
	v_mfma_f32_16x16x32_bf16 v[46:49], v[142:145], v[180:183], v[46:49]
	v_mfma_f32_16x16x32_bf16 v[46:49], v[146:149], v[184:187], v[46:49]
	v_mfma_f32_16x16x32_bf16 v[34:37], v[134:137], v[188:191], v[34:37]
	v_mfma_f32_16x16x32_bf16 v[34:37], v[138:141], v[192:195], v[34:37]
	v_mfma_f32_16x16x32_bf16 v[30:33], v[142:145], v[188:191], v[30:33]
	v_mfma_f32_16x16x32_bf16 v[30:33], v[146:149], v[192:195], v[30:33]
	v_mfma_f32_16x16x32_bf16 v[18:21], v[134:137], v[218:221], v[18:21]
	v_mfma_f32_16x16x32_bf16 v[18:21], v[138:141], v[222:225], v[18:21]
	v_mfma_f32_16x16x32_bf16 v[14:17], v[142:145], v[218:221], v[14:17]
	v_mfma_f32_16x16x32_bf16 v[14:17], v[146:149], v[222:225], v[14:17]
	v_mfma_f32_16x16x32_bf16 v[58:61], v[150:153], v[166:169], v[58:61]
	v_mfma_f32_16x16x32_bf16 v[58:61], v[154:157], v[176:179], v[58:61]
	v_mfma_f32_16x16x32_bf16 v[54:57], v[158:161], v[166:169], v[54:57]
	v_mfma_f32_16x16x32_bf16 v[54:57], v[162:165], v[176:179], v[54:57]
	v_mfma_f32_16x16x32_bf16 v[42:45], v[150:153], v[180:183], v[42:45]
	v_mfma_f32_16x16x32_bf16 v[42:45], v[154:157], v[184:187], v[42:45]
	v_mfma_f32_16x16x32_bf16 v[38:41], v[158:161], v[180:183], v[38:41]
	v_mfma_f32_16x16x32_bf16 v[38:41], v[162:165], v[184:187], v[38:41]
	v_mfma_f32_16x16x32_bf16 v[26:29], v[150:153], v[188:191], v[26:29]
	v_mfma_f32_16x16x32_bf16 v[26:29], v[154:157], v[192:195], v[26:29]
	v_mfma_f32_16x16x32_bf16 v[22:25], v[158:161], v[188:191], v[22:25]
	v_mfma_f32_16x16x32_bf16 v[22:25], v[162:165], v[192:195], v[22:25]
	s_setprio 2
	s_barrier
	v_mfma_f32_16x16x32_bf16 v[10:13], v[150:153], v[218:221], v[10:13]
	v_mfma_f32_16x16x32_bf16 v[10:13], v[154:157], v[222:225], v[10:13]
	v_mfma_f32_16x16x32_bf16 v[4:7], v[158:161], v[218:221], v[6:9]
	v_mfma_f32_16x16x32_bf16 v[4:7], v[162:165], v[222:225], v[4:7]
	s_setprio 0
	s_nop 0
	s_add_i32 s72, 0, 0x18000
	v_add_u32_e32 v3, s72, v213
	s_add_i32 s73, 0, 0x1c000
	ds_read_b128 v[134:137], v3
	ds_read_b128 v[138:141], v3 offset:1024
	ds_read_b128 v[142:145], v3 offset:2048
	ds_read_b128 v[146:149], v3 offset:3072
	v_add_u32_e32 v3, s73, v213
	ds_read_b128 v[150:153], v3
	ds_read_b128 v[154:157], v3 offset:1024
	ds_read_b128 v[158:161], v3 offset:2048
	ds_read_b128 v[162:165], v3 offset:3072
	s_add_u32 s40, s40, 0x40000
	s_addc_u32 s41, s41, 0
	s_mov_b32 m0, s43
	v_lshl_add_u64 v[8:9], s[40:41], 0, v[198:199]
	ds_read_b128 v[166:169], v217 offset:32768
	ds_read_b128 v[176:179], v217 offset:33792
	ds_read_b128 v[180:183], v217 offset:34816
	ds_read_b128 v[184:187], v217 offset:35840
	ds_read_b128 v[188:191], v217 offset:36864
	ds_read_b128 v[192:195], v217 offset:37888
	ds_read_b128 v[218:221], v217 offset:38912
	ds_read_b128 v[222:225], v217 offset:39936
	global_load_lds_dwordx4 v[8:9], off
	v_lshl_add_u64 v[8:9], s[40:41], 0, v[202:203]
	s_mov_b32 m0, s44
	s_nop 0
	global_load_lds_dwordx4 v[8:9], off
	s_waitcnt vmcnt(8)
	s_waitcnt lgkmcnt(0)
	s_barrier
	s_setprio 1
	v_mfma_f32_16x16x32_bf16 v[130:133], v[134:137], v[166:169], v[130:133]
	v_mfma_f32_16x16x32_bf16 v[130:133], v[138:141], v[176:179], v[130:133]
	v_mfma_f32_16x16x32_bf16 v[126:129], v[142:145], v[166:169], v[126:129]
	v_mfma_f32_16x16x32_bf16 v[126:129], v[146:149], v[176:179], v[126:129]
	v_mfma_f32_16x16x32_bf16 v[114:117], v[134:137], v[180:183], v[114:117]
	v_mfma_f32_16x16x32_bf16 v[114:117], v[138:141], v[184:187], v[114:117]
	v_mfma_f32_16x16x32_bf16 v[110:113], v[142:145], v[180:183], v[110:113]
	v_mfma_f32_16x16x32_bf16 v[110:113], v[146:149], v[184:187], v[110:113]
	v_mfma_f32_16x16x32_bf16 v[98:101], v[134:137], v[188:191], v[98:101]
	v_mfma_f32_16x16x32_bf16 v[98:101], v[138:141], v[192:195], v[98:101]
	v_mfma_f32_16x16x32_bf16 v[94:97], v[142:145], v[188:191], v[94:97]
	v_mfma_f32_16x16x32_bf16 v[94:97], v[146:149], v[192:195], v[94:97]
	v_mfma_f32_16x16x32_bf16 v[82:85], v[134:137], v[218:221], v[82:85]
	v_mfma_f32_16x16x32_bf16 v[82:85], v[138:141], v[222:225], v[82:85]
	v_mfma_f32_16x16x32_bf16 v[78:81], v[142:145], v[218:221], v[78:81]
	v_mfma_f32_16x16x32_bf16 v[78:81], v[146:149], v[222:225], v[78:81]
	v_mfma_f32_16x16x32_bf16 v[122:125], v[150:153], v[166:169], v[122:125]
	v_mfma_f32_16x16x32_bf16 v[122:125], v[154:157], v[176:179], v[122:125]
	v_mfma_f32_16x16x32_bf16 v[118:121], v[158:161], v[166:169], v[118:121]
	v_mfma_f32_16x16x32_bf16 v[118:121], v[162:165], v[176:179], v[118:121]
	v_mfma_f32_16x16x32_bf16 v[106:109], v[150:153], v[180:183], v[106:109]
	v_mfma_f32_16x16x32_bf16 v[106:109], v[154:157], v[184:187], v[106:109]
	v_mfma_f32_16x16x32_bf16 v[102:105], v[158:161], v[180:183], v[102:105]
	v_mfma_f32_16x16x32_bf16 v[102:105], v[162:165], v[184:187], v[102:105]
	v_mfma_f32_16x16x32_bf16 v[90:93], v[150:153], v[188:191], v[90:93]
	v_mfma_f32_16x16x32_bf16 v[90:93], v[154:157], v[192:195], v[90:93]
	v_mfma_f32_16x16x32_bf16 v[86:89], v[158:161], v[188:191], v[86:89]
	v_mfma_f32_16x16x32_bf16 v[86:89], v[162:165], v[192:195], v[86:89]
	s_setprio 2
	s_barrier
	v_mfma_f32_16x16x32_bf16 v[74:77], v[150:153], v[218:221], v[74:77]
	v_mfma_f32_16x16x32_bf16 v[74:77], v[154:157], v[222:225], v[74:77]
	v_mfma_f32_16x16x32_bf16 v[70:73], v[158:161], v[218:221], v[70:73]
	v_mfma_f32_16x16x32_bf16 v[70:73], v[162:165], v[222:225], v[70:73]
	s_setprio 0
	s_nop 0
	s_add_i32 s40, s72, s33
	v_lshl_add_u64 v[8:9], v[196:197], 0, s[10:11]
	s_mov_b32 m0, s40
	ds_read_b128 v[166:169], v217 offset:49152
	ds_read_b128 v[176:179], v217 offset:50176
	ds_read_b128 v[180:183], v217 offset:51200
	ds_read_b128 v[184:187], v217 offset:52224
	ds_read_b128 v[188:191], v217 offset:53248
	ds_read_b128 v[192:195], v217 offset:54272
	ds_read_b128 v[218:221], v217 offset:55296
	ds_read_b128 v[222:225], v217 offset:56320
	global_load_lds_dwordx4 v[8:9], off
	s_add_i32 m0, s40, 0x2000
	s_add_u32 s4, s4, 0x40080
	v_lshl_add_u64 v[8:9], v[210:211], 0, s[10:11]
	s_addc_u32 s5, s5, 0
	s_add_i32 s40, s73, s33
	global_load_lds_dwordx4 v[8:9], off
	v_lshl_add_u64 v[8:9], s[4:5], 0, v[200:201]
	s_mov_b32 m0, s40
	s_nop 0
	global_load_lds_dwordx4 v[8:9], off
	v_lshl_add_u64 v[8:9], s[4:5], 0, v[204:205]
	s_add_i32 m0, s40, 0x2000
	s_nop 0
	global_load_lds_dwordx4 v[8:9], off
	v_lshl_add_u64 v[8:9], v[226:227], 0, s[10:11]
	s_mov_b32 m0, s47
	s_nop 0
	global_load_lds_dwordx4 v[8:9], off
	v_lshl_add_u64 v[8:9], v[230:231], 0, s[10:11]
	s_mov_b32 m0, s48
	s_nop 0
	global_load_lds_dwordx4 v[8:9], off
	s_waitcnt vmcnt(8)
	s_waitcnt lgkmcnt(0)
	s_barrier
	s_setprio 1
	v_mfma_f32_16x16x32_bf16 v[66:69], v[134:137], v[166:169], v[66:69]
	v_mfma_f32_16x16x32_bf16 v[66:69], v[138:141], v[176:179], v[66:69]
	v_mfma_f32_16x16x32_bf16 v[62:65], v[142:145], v[166:169], v[62:65]
	v_mfma_f32_16x16x32_bf16 v[62:65], v[146:149], v[176:179], v[62:65]
	v_mfma_f32_16x16x32_bf16 v[50:53], v[134:137], v[180:183], v[50:53]
	v_mfma_f32_16x16x32_bf16 v[50:53], v[138:141], v[184:187], v[50:53]
	v_mfma_f32_16x16x32_bf16 v[46:49], v[142:145], v[180:183], v[46:49]
	v_mfma_f32_16x16x32_bf16 v[46:49], v[146:149], v[184:187], v[46:49]
	v_mfma_f32_16x16x32_bf16 v[34:37], v[134:137], v[188:191], v[34:37]
	v_mfma_f32_16x16x32_bf16 v[34:37], v[138:141], v[192:195], v[34:37]
	v_mfma_f32_16x16x32_bf16 v[30:33], v[142:145], v[188:191], v[30:33]
	v_mfma_f32_16x16x32_bf16 v[30:33], v[146:149], v[192:195], v[30:33]
	v_mfma_f32_16x16x32_bf16 v[18:21], v[134:137], v[218:221], v[18:21]
	v_mfma_f32_16x16x32_bf16 v[18:21], v[138:141], v[222:225], v[18:21]
	v_mfma_f32_16x16x32_bf16 v[14:17], v[142:145], v[218:221], v[14:17]
	v_mfma_f32_16x16x32_bf16 v[14:17], v[146:149], v[222:225], v[14:17]
	v_mfma_f32_16x16x32_bf16 v[58:61], v[150:153], v[166:169], v[58:61]
	v_mfma_f32_16x16x32_bf16 v[58:61], v[154:157], v[176:179], v[58:61]
	v_mfma_f32_16x16x32_bf16 v[54:57], v[158:161], v[166:169], v[54:57]
	v_mfma_f32_16x16x32_bf16 v[54:57], v[162:165], v[176:179], v[54:57]
	v_mfma_f32_16x16x32_bf16 v[42:45], v[150:153], v[180:183], v[42:45]
	v_mfma_f32_16x16x32_bf16 v[42:45], v[154:157], v[184:187], v[42:45]
	v_mfma_f32_16x16x32_bf16 v[38:41], v[158:161], v[180:183], v[38:41]
	v_mfma_f32_16x16x32_bf16 v[38:41], v[162:165], v[184:187], v[38:41]
	v_mfma_f32_16x16x32_bf16 v[26:29], v[150:153], v[188:191], v[26:29]
	v_mfma_f32_16x16x32_bf16 v[26:29], v[154:157], v[192:195], v[26:29]
	v_mfma_f32_16x16x32_bf16 v[22:25], v[158:161], v[188:191], v[22:25]
	v_mfma_f32_16x16x32_bf16 v[22:25], v[162:165], v[192:195], v[22:25]
	s_setprio 2
	s_barrier
	v_mfma_f32_16x16x32_bf16 v[8:11], v[150:153], v[218:221], v[10:13]
	v_mfma_f32_16x16x32_bf16 v[10:13], v[154:157], v[222:225], v[8:11]
	v_mfma_f32_16x16x32_bf16 v[4:7], v[158:161], v[218:221], v[4:7]
	v_mfma_f32_16x16x32_bf16 v[6:9], v[162:165], v[222:225], v[4:7]
	s_setprio 0
	s_nop 0
	s_add_i32 s67, s67, 2
	s_add_u32 s38, s38, 0x100
	s_addc_u32 s39, s39, 0
	s_cmp_gt_u32 s67, 13
	s_cbranch_scc1 .LBB0_590

.LBB0_760:
	ds_read_b128 v[114:117], v232
	ds_read_b128 v[118:121], v232 offset:1024
	ds_read_b128 v[130:133], v232 offset:2048
	ds_read_b128 v[138:141], v232 offset:3072
	ds_read_b128 v[146:149], v233
	ds_read_b128 v[150:153], v233 offset:1024
	ds_read_b128 v[154:157], v233 offset:2048
	ds_read_b128 v[158:161], v233 offset:3072
	s_add_u32 s30, s28, 0xfffc0080
	s_addc_u32 s31, s29, -1
	s_cmp_eq_u32 s47, 12
	s_cselect_b32 s35, s3, s31
	s_cselect_b32 s34, s17, s30
	s_cselect_b32 s31, s19, s46
	s_cselect_b32 s30, s27, s45
	v_lshl_add_u64 v[206:207], s[28:29], 0, v[202:203]
	s_add_i32 m0, s36, 0xc000
	ds_read_b128 v[162:165], v234
	ds_read_b128 v[166:169], v234 offset:1024
	ds_read_b128 v[170:173], v234 offset:2048
	ds_read_b128 v[174:177], v234 offset:3072
	ds_read_b128 v[178:181], v234 offset:4096
	ds_read_b128 v[182:185], v234 offset:5120
	ds_read_b128 v[186:189], v234 offset:6144
	ds_read_b128 v[190:193], v234 offset:7168
	global_load_lds_dwordx4 v[206:207], off
	v_lshl_add_u64 v[206:207], s[28:29], 0, v[204:205]
	s_add_i32 m0, s36, 0xe000
	s_nop 0
	global_load_lds_dwordx4 v[206:207], off
	s_waitcnt vmcnt(8)
	s_waitcnt lgkmcnt(0)
	s_barrier
	s_setprio 1
	v_mfma_f32_16x16x32_bf16 v[142:145], v[114:117], v[162:165], v[142:145]
	v_mfma_f32_16x16x32_bf16 v[142:145], v[118:121], v[166:169], v[142:145]
	v_mfma_f32_16x16x32_bf16 v[134:137], v[130:133], v[162:165], v[134:137]
	v_mfma_f32_16x16x32_bf16 v[134:137], v[138:141], v[166:169], v[134:137]
	v_mfma_f32_16x16x32_bf16 v[110:113], v[114:117], v[170:173], v[110:113]
	v_mfma_f32_16x16x32_bf16 v[110:113], v[118:121], v[174:177], v[110:113]
	v_mfma_f32_16x16x32_bf16 v[106:109], v[130:133], v[170:173], v[106:109]
	v_mfma_f32_16x16x32_bf16 v[106:109], v[138:141], v[174:177], v[106:109]
	v_mfma_f32_16x16x32_bf16 v[94:97], v[114:117], v[178:181], v[94:97]
	v_mfma_f32_16x16x32_bf16 v[94:97], v[118:121], v[182:185], v[94:97]
	v_mfma_f32_16x16x32_bf16 v[90:93], v[130:133], v[178:181], v[90:93]
	v_mfma_f32_16x16x32_bf16 v[90:93], v[138:141], v[182:185], v[90:93]
	v_mfma_f32_16x16x32_bf16 v[78:81], v[114:117], v[186:189], v[78:81]
	v_mfma_f32_16x16x32_bf16 v[78:81], v[118:121], v[190:193], v[78:81]
	v_mfma_f32_16x16x32_bf16 v[74:77], v[130:133], v[186:189], v[74:77]
	v_mfma_f32_16x16x32_bf16 v[74:77], v[138:141], v[190:193], v[74:77]
	v_mfma_f32_16x16x32_bf16 v[126:129], v[146:149], v[162:165], v[126:129]
	v_mfma_f32_16x16x32_bf16 v[126:129], v[150:153], v[166:169], v[126:129]
	v_mfma_f32_16x16x32_bf16 v[122:125], v[154:157], v[162:165], v[122:125]
	v_mfma_f32_16x16x32_bf16 v[122:125], v[158:161], v[166:169], v[122:125]
	v_mfma_f32_16x16x32_bf16 v[102:105], v[146:149], v[170:173], v[102:105]
	v_mfma_f32_16x16x32_bf16 v[102:105], v[150:153], v[174:177], v[102:105]
	v_mfma_f32_16x16x32_bf16 v[98:101], v[154:157], v[170:173], v[98:101]
	v_mfma_f32_16x16x32_bf16 v[98:101], v[158:161], v[174:177], v[98:101]
	v_mfma_f32_16x16x32_bf16 v[86:89], v[146:149], v[178:181], v[86:89]
	v_mfma_f32_16x16x32_bf16 v[86:89], v[150:153], v[182:185], v[86:89]
	v_mfma_f32_16x16x32_bf16 v[82:85], v[154:157], v[178:181], v[82:85]
	v_mfma_f32_16x16x32_bf16 v[82:85], v[158:161], v[182:185], v[82:85]
	s_setprio 2
	s_barrier
	v_mfma_f32_16x16x32_bf16 v[70:73], v[146:149], v[186:189], v[70:73]
	v_mfma_f32_16x16x32_bf16 v[70:73], v[150:153], v[190:193], v[70:73]
	v_mfma_f32_16x16x32_bf16 v[66:69], v[154:157], v[186:189], v[66:69]
	v_mfma_f32_16x16x32_bf16 v[66:69], v[158:161], v[190:193], v[66:69]
	s_setprio 0
	s_nop 0
	s_add_i32 s48, s43, s33
	v_lshl_add_u64 v[206:207], s[30:31], 0, v[196:197]
	s_mov_b32 m0, s48
	ds_read_b128 v[162:165], v234 offset:16384
	ds_read_b128 v[166:169], v234 offset:17408
	ds_read_b128 v[170:173], v234 offset:18432
	ds_read_b128 v[174:177], v234 offset:19456
	ds_read_b128 v[178:181], v234 offset:20480
	ds_read_b128 v[182:185], v234 offset:21504
	ds_read_b128 v[186:189], v234 offset:22528
	ds_read_b128 v[190:193], v234 offset:23552
	global_load_lds_dwordx4 v[206:207], off
	s_add_i32 m0, s48, 0x2000
	s_add_u32 s48, s30, 0x40000
	v_lshl_add_u64 v[208:209], s[30:31], 0, v[200:201]
	s_addc_u32 s49, s31, 0
	s_add_i32 s50, s44, s33
	global_load_lds_dwordx4 v[208:209], off
	v_lshl_add_u64 v[210:211], s[48:49], 0, v[196:197]
	s_mov_b32 m0, s50
	v_lshl_add_u64 v[212:213], s[34:35], 0, v[198:199]
	global_load_lds_dwordx4 v[210:211], off
	v_lshl_add_u64 v[210:211], s[48:49], 0, v[200:201]
	s_add_i32 m0, s50, 0x2000
	s_nop 0
	global_load_lds_dwordx4 v[210:211], off
	v_lshl_add_u64 v[210:211], s[34:35], 0, v[194:195]
	s_mov_b32 m0, s36
	s_nop 0
	global_load_lds_dwordx4 v[210:211], off
	s_mov_b32 m0, s37
	s_nop 0
	global_load_lds_dwordx4 v[212:213], off
	s_waitcnt vmcnt(8)
	s_waitcnt lgkmcnt(0)
	s_barrier
	s_setprio 1
	v_mfma_f32_16x16x32_bf16 v[62:65], v[114:117], v[162:165], v[62:65]
	v_mfma_f32_16x16x32_bf16 v[62:65], v[118:121], v[166:169], v[62:65]
	v_mfma_f32_16x16x32_bf16 v[58:61], v[130:133], v[162:165], v[58:61]
	v_mfma_f32_16x16x32_bf16 v[58:61], v[138:141], v[166:169], v[58:61]
	v_mfma_f32_16x16x32_bf16 v[46:49], v[114:117], v[170:173], v[46:49]
	v_mfma_f32_16x16x32_bf16 v[46:49], v[118:121], v[174:177], v[46:49]
	v_mfma_f32_16x16x32_bf16 v[42:45], v[130:133], v[170:173], v[42:45]
	v_mfma_f32_16x16x32_bf16 v[42:45], v[138:141], v[174:177], v[42:45]
	v_mfma_f32_16x16x32_bf16 v[30:33], v[114:117], v[178:181], v[30:33]
	v_mfma_f32_16x16x32_bf16 v[30:33], v[118:121], v[182:185], v[30:33]
	v_mfma_f32_16x16x32_bf16 v[26:29], v[130:133], v[178:181], v[26:29]
	v_mfma_f32_16x16x32_bf16 v[26:29], v[138:141], v[182:185], v[26:29]
	v_mfma_f32_16x16x32_bf16 v[14:17], v[114:117], v[186:189], v[14:17]
	v_mfma_f32_16x16x32_bf16 v[14:17], v[118:121], v[190:193], v[14:17]
	v_mfma_f32_16x16x32_bf16 v[10:13], v[130:133], v[186:189], v[10:13]
	v_mfma_f32_16x16x32_bf16 v[10:13], v[138:141], v[190:193], v[10:13]
	v_mfma_f32_16x16x32_bf16 v[54:57], v[146:149], v[162:165], v[54:57]
	v_mfma_f32_16x16x32_bf16 v[54:57], v[150:153], v[166:169], v[54:57]
	v_mfma_f32_16x16x32_bf16 v[50:53], v[154:157], v[162:165], v[50:53]
	v_mfma_f32_16x16x32_bf16 v[50:53], v[158:161], v[166:169], v[50:53]
	v_mfma_f32_16x16x32_bf16 v[38:41], v[146:149], v[170:173], v[38:41]
	v_mfma_f32_16x16x32_bf16 v[38:41], v[150:153], v[174:177], v[38:41]
	v_mfma_f32_16x16x32_bf16 v[34:37], v[154:157], v[170:173], v[34:37]
	v_mfma_f32_16x16x32_bf16 v[34:37], v[158:161], v[174:177], v[34:37]
	v_mfma_f32_16x16x32_bf16 v[22:25], v[146:149], v[178:181], v[22:25]
	v_mfma_f32_16x16x32_bf16 v[22:25], v[150:153], v[182:185], v[22:25]
	v_mfma_f32_16x16x32_bf16 v[18:21], v[154:157], v[178:181], v[18:21]
	v_mfma_f32_16x16x32_bf16 v[18:21], v[158:161], v[182:185], v[18:21]
	s_setprio 2
	s_barrier
	v_mfma_f32_16x16x32_bf16 v[6:9], v[146:149], v[186:189], v[6:9]
	v_mfma_f32_16x16x32_bf16 v[6:9], v[150:153], v[190:193], v[6:9]
	v_mfma_f32_16x16x32_bf16 v[2:5], v[154:157], v[186:189], v[2:5]
	v_mfma_f32_16x16x32_bf16 v[2:5], v[158:161], v[190:193], v[2:5]
	s_setprio 0
	s_nop 0
	s_add_i32 s48, 0, 0x18000
	s_add_i32 s49, 0, 0x1c000
	v_add_u32_e32 v138, s48, v230
	v_add_u32_e32 v158, s49, v230
	ds_read_b128 v[114:117], v138
	ds_read_b128 v[118:121], v138 offset:1024
	ds_read_b128 v[130:133], v138 offset:2048
	ds_read_b128 v[138:141], v138 offset:3072
	ds_read_b128 v[146:149], v158
	ds_read_b128 v[150:153], v158 offset:1024
	ds_read_b128 v[154:157], v158 offset:2048
	ds_read_b128 v[158:161], v158 offset:3072
	s_add_u32 s34, s34, 0x40000
	s_addc_u32 s35, s35, 0
	s_mov_b32 m0, s38
	v_lshl_add_u64 v[214:215], s[34:35], 0, v[194:195]
	ds_read_b128 v[162:165], v234 offset:32768
	ds_read_b128 v[166:169], v234 offset:33792
	ds_read_b128 v[170:173], v234 offset:34816
	ds_read_b128 v[174:177], v234 offset:35840
	ds_read_b128 v[178:181], v234 offset:36864
	ds_read_b128 v[182:185], v234 offset:37888
	ds_read_b128 v[186:189], v234 offset:38912
	ds_read_b128 v[190:193], v234 offset:39936
	global_load_lds_dwordx4 v[214:215], off
	v_lshl_add_u64 v[214:215], s[34:35], 0, v[198:199]
	s_mov_b32 m0, s39
	s_nop 0
	global_load_lds_dwordx4 v[214:215], off
	s_waitcnt vmcnt(8)
	s_waitcnt lgkmcnt(0)
	s_barrier
	s_setprio 1
	v_mfma_f32_16x16x32_bf16 v[142:145], v[114:117], v[162:165], v[142:145]
	v_mfma_f32_16x16x32_bf16 v[142:145], v[118:121], v[166:169], v[142:145]
	v_mfma_f32_16x16x32_bf16 v[134:137], v[130:133], v[162:165], v[134:137]
	v_mfma_f32_16x16x32_bf16 v[134:137], v[138:141], v[166:169], v[134:137]
	v_mfma_f32_16x16x32_bf16 v[110:113], v[114:117], v[170:173], v[110:113]
	v_mfma_f32_16x16x32_bf16 v[110:113], v[118:121], v[174:177], v[110:113]
	v_mfma_f32_16x16x32_bf16 v[106:109], v[130:133], v[170:173], v[106:109]
	v_mfma_f32_16x16x32_bf16 v[106:109], v[138:141], v[174:177], v[106:109]
	v_mfma_f32_16x16x32_bf16 v[94:97], v[114:117], v[178:181], v[94:97]
	v_mfma_f32_16x16x32_bf16 v[94:97], v[118:121], v[182:185], v[94:97]
	v_mfma_f32_16x16x32_bf16 v[90:93], v[130:133], v[178:181], v[90:93]
	v_mfma_f32_16x16x32_bf16 v[90:93], v[138:141], v[182:185], v[90:93]
	v_mfma_f32_16x16x32_bf16 v[78:81], v[114:117], v[186:189], v[78:81]
	v_mfma_f32_16x16x32_bf16 v[78:81], v[118:121], v[190:193], v[78:81]
	v_mfma_f32_16x16x32_bf16 v[74:77], v[130:133], v[186:189], v[74:77]
	v_mfma_f32_16x16x32_bf16 v[74:77], v[138:141], v[190:193], v[74:77]
	v_mfma_f32_16x16x32_bf16 v[126:129], v[146:149], v[162:165], v[126:129]
	v_mfma_f32_16x16x32_bf16 v[126:129], v[150:153], v[166:169], v[126:129]
	v_mfma_f32_16x16x32_bf16 v[122:125], v[154:157], v[162:165], v[122:125]
	v_mfma_f32_16x16x32_bf16 v[122:125], v[158:161], v[166:169], v[122:125]
	v_mfma_f32_16x16x32_bf16 v[102:105], v[146:149], v[170:173], v[102:105]
	v_mfma_f32_16x16x32_bf16 v[102:105], v[150:153], v[174:177], v[102:105]
	v_mfma_f32_16x16x32_bf16 v[98:101], v[154:157], v[170:173], v[98:101]
	v_mfma_f32_16x16x32_bf16 v[98:101], v[158:161], v[174:177], v[98:101]
	v_mfma_f32_16x16x32_bf16 v[86:89], v[146:149], v[178:181], v[86:89]
	v_mfma_f32_16x16x32_bf16 v[86:89], v[150:153], v[182:185], v[86:89]
	v_mfma_f32_16x16x32_bf16 v[82:85], v[154:157], v[178:181], v[82:85]
	v_mfma_f32_16x16x32_bf16 v[82:85], v[158:161], v[182:185], v[82:85]
	s_setprio 2
	s_barrier
	v_mfma_f32_16x16x32_bf16 v[70:73], v[146:149], v[186:189], v[70:73]
	v_mfma_f32_16x16x32_bf16 v[70:73], v[150:153], v[190:193], v[70:73]
	v_mfma_f32_16x16x32_bf16 v[66:69], v[154:157], v[186:189], v[66:69]
	v_mfma_f32_16x16x32_bf16 v[66:69], v[158:161], v[190:193], v[66:69]
	s_setprio 0
	s_nop 0
	s_add_i32 s34, s48, s33
	v_lshl_add_u64 v[206:207], v[206:207], 0, s[8:9]
	s_mov_b32 m0, s34
	ds_read_b128 v[162:165], v234 offset:49152
	ds_read_b128 v[166:169], v234 offset:50176
	ds_read_b128 v[170:173], v234 offset:51200
	ds_read_b128 v[174:177], v234 offset:52224
	ds_read_b128 v[178:181], v234 offset:53248
	ds_read_b128 v[182:185], v234 offset:54272
	ds_read_b128 v[186:189], v234 offset:55296
	ds_read_b128 v[190:193], v234 offset:56320
	global_load_lds_dwordx4 v[206:207], off
	s_add_i32 m0, s34, 0x2000
	s_add_u32 s30, s30, 0x40080
	v_lshl_add_u64 v[206:207], v[208:209], 0, s[8:9]
	s_addc_u32 s31, s31, 0
	s_add_i32 s34, s49, s33
	global_load_lds_dwordx4 v[206:207], off
	v_lshl_add_u64 v[206:207], s[30:31], 0, v[196:197]
	s_mov_b32 m0, s34
	s_nop 0
	global_load_lds_dwordx4 v[206:207], off
	v_lshl_add_u64 v[206:207], s[30:31], 0, v[200:201]
	s_add_i32 m0, s34, 0x2000
	s_nop 0
	global_load_lds_dwordx4 v[206:207], off
	v_lshl_add_u64 v[206:207], v[210:211], 0, s[8:9]
	s_mov_b32 m0, s40
	s_nop 0
	global_load_lds_dwordx4 v[206:207], off
	v_lshl_add_u64 v[206:207], v[212:213], 0, s[8:9]
	s_mov_b32 m0, s41
	s_nop 0
	global_load_lds_dwordx4 v[206:207], off
	s_waitcnt vmcnt(8)
	s_waitcnt lgkmcnt(0)
	s_barrier
	s_setprio 1
	v_mfma_f32_16x16x32_bf16 v[62:65], v[114:117], v[162:165], v[62:65]
	v_mfma_f32_16x16x32_bf16 v[62:65], v[118:121], v[166:169], v[62:65]
	v_mfma_f32_16x16x32_bf16 v[58:61], v[130:133], v[162:165], v[58:61]
	v_mfma_f32_16x16x32_bf16 v[58:61], v[138:141], v[166:169], v[58:61]
	v_mfma_f32_16x16x32_bf16 v[46:49], v[114:117], v[170:173], v[46:49]
	v_mfma_f32_16x16x32_bf16 v[46:49], v[118:121], v[174:177], v[46:49]
	v_mfma_f32_16x16x32_bf16 v[42:45], v[130:133], v[170:173], v[42:45]
	v_mfma_f32_16x16x32_bf16 v[42:45], v[138:141], v[174:177], v[42:45]
	v_mfma_f32_16x16x32_bf16 v[30:33], v[114:117], v[178:181], v[30:33]
	v_mfma_f32_16x16x32_bf16 v[30:33], v[118:121], v[182:185], v[30:33]
	v_mfma_f32_16x16x32_bf16 v[26:29], v[130:133], v[178:181], v[26:29]
	v_mfma_f32_16x16x32_bf16 v[26:29], v[138:141], v[182:185], v[26:29]
	v_mfma_f32_16x16x32_bf16 v[14:17], v[114:117], v[186:189], v[14:17]
	v_mfma_f32_16x16x32_bf16 v[14:17], v[118:121], v[190:193], v[14:17]
	v_mfma_f32_16x16x32_bf16 v[10:13], v[130:133], v[186:189], v[10:13]
	v_mfma_f32_16x16x32_bf16 v[10:13], v[138:141], v[190:193], v[10:13]
	v_mfma_f32_16x16x32_bf16 v[54:57], v[146:149], v[162:165], v[54:57]
	v_mfma_f32_16x16x32_bf16 v[54:57], v[150:153], v[166:169], v[54:57]
	v_mfma_f32_16x16x32_bf16 v[50:53], v[154:157], v[162:165], v[50:53]
	v_mfma_f32_16x16x32_bf16 v[50:53], v[158:161], v[166:169], v[50:53]
	v_mfma_f32_16x16x32_bf16 v[38:41], v[146:149], v[170:173], v[38:41]
	v_mfma_f32_16x16x32_bf16 v[38:41], v[150:153], v[174:177], v[38:41]
	v_mfma_f32_16x16x32_bf16 v[34:37], v[154:157], v[170:173], v[34:37]
	v_mfma_f32_16x16x32_bf16 v[34:37], v[158:161], v[174:177], v[34:37]
	v_mfma_f32_16x16x32_bf16 v[22:25], v[146:149], v[178:181], v[22:25]
	v_mfma_f32_16x16x32_bf16 v[22:25], v[150:153], v[182:185], v[22:25]
	v_mfma_f32_16x16x32_bf16 v[18:21], v[154:157], v[178:181], v[18:21]
	v_mfma_f32_16x16x32_bf16 v[18:21], v[158:161], v[182:185], v[18:21]
	s_setprio 2
	s_barrier
	v_mfma_f32_16x16x32_bf16 v[6:9], v[146:149], v[186:189], v[6:9]
	v_mfma_f32_16x16x32_bf16 v[6:9], v[150:153], v[190:193], v[6:9]
	v_mfma_f32_16x16x32_bf16 v[2:5], v[154:157], v[186:189], v[2:5]
	v_mfma_f32_16x16x32_bf16 v[2:5], v[158:161], v[190:193], v[2:5]
	s_setprio 0
	s_nop 0
	s_add_i32 s47, s47, 2
	s_add_u32 s28, s28, 0x100
	s_addc_u32 s29, s29, 0
	s_add_u32 s45, s45, 0x100
	s_addc_u32 s46, s46, 0
	s_cmp_gt_u32 s47, 13
	s_cbranch_scc0 .LBB0_760
	s_and_b64 vcc, exec, s[10:11]
	s_cbranch_vccz .LBB0_763
	s_barrier

.LBB0_944:
	s_ashr_i32 s9, s8, 31
	s_lshl_b64 s[14:15], s[8:9], 19
	s_add_u32 s14, s64, s14
	s_addc_u32 s15, s65, s15
	s_and_b64 s[16:17], s[12:13], exec
	s_cselect_b32 s9, s15, s19
	s_cselect_b32 s39, s14, s18
	s_ashr_i32 s11, s10, 31
	s_lshl_b64 s[16:17], s[10:11], 19
	v_readlane_b32 s24, v245, 3
	v_readlane_b32 s25, v245, 4
	s_add_u32 s16, s24, s16
	s_addc_u32 s17, s25, s17
	s_and_b64 s[24:25], s[12:13], exec
	s_cselect_b32 s40, s17, s23
	s_cselect_b32 s41, s16, s22
	s_lshl_b32 s11, s20, 8
	s_add_u32 s42, s22, 0x100
	v_mov_b32_e32 v2, 0
	v_or_b32_e32 v146, s11, v228
	v_lshl_add_u64 v[142:143], s[18:19], 0, v[138:139]
	v_lshl_add_u64 v[144:145], s[18:19], 0, v[140:141]
	s_addc_u32 s43, s23, 0
	s_mov_b32 s44, -2
	s_mov_b64 s[20:21], 0
	ds_read_b128 v[154:157], v229
	ds_read_b128 v[158:161], v229 offset:1024
	ds_read_b128 v[162:165], v229 offset:2048
	ds_read_b128 v[166:169], v229 offset:3072
	s_add_u32 s22, s18, s20
	ds_read_b128 v[170:173], v229 offset:16384
	ds_read_b128 v[174:177], v229 offset:17408
	ds_read_b128 v[178:181], v229 offset:18432
	ds_read_b128 v[182:185], v229 offset:19456
	s_addc_u32 s23, s19, s21
	s_add_u32 s22, s22, 0x100
	s_addc_u32 s23, s23, 0
	s_add_u32 s45, s42, s20
	s_addc_u32 s46, s43, s21
	s_cmpk_eq_i32 s20, 0x700
	s_cselect_b32 s25, s9, s23
	s_cselect_b32 s24, s39, s22
	s_cselect_b32 s23, s40, s46
	s_cselect_b32 s22, s41, s45
	s_add_u32 s48, s18, s20
	s_addc_u32 s49, s19, s21
	s_add_i32 m0, s27, 0xc000
	ds_read_b128 v[186:189], v152
	ds_read_b128 v[190:193], v152 offset:1024
	ds_read_b128 v[194:197], v152 offset:2048
	ds_read_b128 v[198:201], v152 offset:3072
	ds_read_b128 v[202:205], v152 offset:4096
	ds_read_b128 v[206:209], v152 offset:5120
	ds_read_b128 v[210:213], v152 offset:6144
	ds_read_b128 v[214:217], v152 offset:7168
	global_load_lds_dwordx4 v138, s[48:49]
	s_add_i32 m0, s27, 0xe000
	s_nop 0
	global_load_lds_dwordx4 v140, s[48:49]
	s_waitcnt vmcnt(8)
	s_waitcnt lgkmcnt(0)
	s_barrier
	s_setprio 1
	v_mfma_f32_16x16x32_bf16 v[126:129], v[154:157], v[186:189], 0
	v_mfma_f32_16x16x32_bf16 v[126:129], v[158:161], v[190:193], v[126:129]
	v_mfma_f32_16x16x32_bf16 v[118:121], v[162:165], v[186:189], 0
	v_mfma_f32_16x16x32_bf16 v[118:121], v[166:169], v[190:193], v[118:121]
	v_mfma_f32_16x16x32_bf16 v[110:113], v[154:157], v[194:197], 0
	v_mfma_f32_16x16x32_bf16 v[110:113], v[158:161], v[198:201], v[110:113]
	v_mfma_f32_16x16x32_bf16 v[102:105], v[162:165], v[194:197], 0
	v_mfma_f32_16x16x32_bf16 v[102:105], v[166:169], v[198:201], v[102:105]
	v_mfma_f32_16x16x32_bf16 v[94:97], v[154:157], v[202:205], 0
	v_mfma_f32_16x16x32_bf16 v[94:97], v[158:161], v[206:209], v[94:97]
	v_mfma_f32_16x16x32_bf16 v[86:89], v[162:165], v[202:205], 0
	v_mfma_f32_16x16x32_bf16 v[86:89], v[166:169], v[206:209], v[86:89]
	v_mfma_f32_16x16x32_bf16 v[78:81], v[154:157], v[210:213], 0
	v_mfma_f32_16x16x32_bf16 v[78:81], v[158:161], v[214:217], v[78:81]
	v_mfma_f32_16x16x32_bf16 v[70:73], v[162:165], v[210:213], 0
	v_mfma_f32_16x16x32_bf16 v[70:73], v[166:169], v[214:217], v[70:73]
	v_mfma_f32_16x16x32_bf16 v[122:125], v[170:173], v[186:189], 0
	v_mfma_f32_16x16x32_bf16 v[122:125], v[174:177], v[190:193], v[122:125]
	v_mfma_f32_16x16x32_bf16 v[114:117], v[178:181], v[186:189], 0
	v_mfma_f32_16x16x32_bf16 v[114:117], v[182:185], v[190:193], v[114:117]
	v_mfma_f32_16x16x32_bf16 v[106:109], v[170:173], v[194:197], 0
	v_mfma_f32_16x16x32_bf16 v[106:109], v[174:177], v[198:201], v[106:109]
	v_mfma_f32_16x16x32_bf16 v[98:101], v[178:181], v[194:197], 0
	v_mfma_f32_16x16x32_bf16 v[98:101], v[182:185], v[198:201], v[98:101]
	v_mfma_f32_16x16x32_bf16 v[90:93], v[170:173], v[202:205], 0
	v_mfma_f32_16x16x32_bf16 v[90:93], v[174:177], v[206:209], v[90:93]
	v_mfma_f32_16x16x32_bf16 v[82:85], v[178:181], v[202:205], 0
	v_mfma_f32_16x16x32_bf16 v[82:85], v[182:185], v[206:209], v[82:85]
	s_setprio 2
	s_barrier
	v_mfma_f32_16x16x32_bf16 v[74:77], v[170:173], v[210:213], 0
	v_mfma_f32_16x16x32_bf16 v[74:77], v[174:177], v[214:217], v[74:77]
	v_mfma_f32_16x16x32_bf16 v[66:69], v[178:181], v[210:213], 0
	v_mfma_f32_16x16x32_bf16 v[66:69], v[182:185], v[214:217], v[66:69]
	s_setprio 0
	s_nop 0
	s_add_i32 s45, s35, s26
	s_add_u32 s50, s22, 0x80
	s_addc_u32 s51, s23, 0
	s_add_u32 s52, s24, 0x80
	s_addc_u32 s53, s25, 0
	s_mov_b32 m0, s45
	ds_read_b128 v[186:189], v152 offset:16384
	ds_read_b128 v[190:193], v152 offset:17408
	ds_read_b128 v[194:197], v152 offset:18432
	ds_read_b128 v[198:201], v152 offset:19456
	ds_read_b128 v[202:205], v152 offset:20480
	ds_read_b128 v[206:209], v152 offset:21504
	ds_read_b128 v[210:213], v152 offset:22528
	ds_read_b128 v[214:217], v152 offset:23552
	global_load_lds_dwordx4 v134, s[22:23]
	s_add_i32 m0, s45, 0x2000
	s_add_u32 s46, s22, 0x40000
	s_addc_u32 s47, s23, 0
	s_add_i32 s45, s36, s26
	global_load_lds_dwordx4 v130, s[22:23]
	s_mov_b32 m0, s45
	s_nop 0
	global_load_lds_dwordx4 v134, s[46:47]
	s_add_i32 m0, s45, 0x2000
	s_nop 0
	global_load_lds_dwordx4 v130, s[46:47]
	s_mov_b32 m0, s27
	s_nop 0
	global_load_lds_dwordx4 v136, s[24:25]
	s_mov_b32 m0, s28
	s_nop 0
	global_load_lds_dwordx4 v132, s[24:25]
	s_waitcnt vmcnt(8)
	s_waitcnt lgkmcnt(0)
	s_barrier
	s_setprio 1
	v_mfma_f32_16x16x32_bf16 v[62:65], v[154:157], v[186:189], 0
	v_mfma_f32_16x16x32_bf16 v[62:65], v[158:161], v[190:193], v[62:65]
	v_mfma_f32_16x16x32_bf16 v[54:57], v[162:165], v[186:189], 0
	v_mfma_f32_16x16x32_bf16 v[54:57], v[166:169], v[190:193], v[54:57]
	v_mfma_f32_16x16x32_bf16 v[46:49], v[154:157], v[194:197], 0
	v_mfma_f32_16x16x32_bf16 v[46:49], v[158:161], v[198:201], v[46:49]
	v_mfma_f32_16x16x32_bf16 v[38:41], v[162:165], v[194:197], 0
	v_mfma_f32_16x16x32_bf16 v[38:41], v[166:169], v[198:201], v[38:41]
	v_mfma_f32_16x16x32_bf16 v[30:33], v[154:157], v[202:205], 0
	v_mfma_f32_16x16x32_bf16 v[30:33], v[158:161], v[206:209], v[30:33]
	v_mfma_f32_16x16x32_bf16 v[22:25], v[162:165], v[202:205], 0
	v_mfma_f32_16x16x32_bf16 v[22:25], v[166:169], v[206:209], v[22:25]
	v_mfma_f32_16x16x32_bf16 v[14:17], v[154:157], v[210:213], 0
	v_mfma_f32_16x16x32_bf16 v[14:17], v[158:161], v[214:217], v[14:17]
	v_mfma_f32_16x16x32_bf16 v[6:9], v[162:165], v[210:213], 0
	v_mfma_f32_16x16x32_bf16 v[6:9], v[166:169], v[214:217], v[6:9]
	v_mfma_f32_16x16x32_bf16 v[58:61], v[170:173], v[186:189], 0
	v_mfma_f32_16x16x32_bf16 v[58:61], v[174:177], v[190:193], v[58:61]
	v_mfma_f32_16x16x32_bf16 v[50:53], v[178:181], v[186:189], 0
	v_mfma_f32_16x16x32_bf16 v[50:53], v[182:185], v[190:193], v[50:53]
	v_mfma_f32_16x16x32_bf16 v[42:45], v[170:173], v[194:197], 0
	v_mfma_f32_16x16x32_bf16 v[42:45], v[174:177], v[198:201], v[42:45]
	v_mfma_f32_16x16x32_bf16 v[34:37], v[178:181], v[194:197], 0
	v_mfma_f32_16x16x32_bf16 v[34:37], v[182:185], v[198:201], v[34:37]
	v_mfma_f32_16x16x32_bf16 v[26:29], v[170:173], v[202:205], 0
	v_mfma_f32_16x16x32_bf16 v[26:29], v[174:177], v[206:209], v[26:29]
	v_mfma_f32_16x16x32_bf16 v[18:21], v[178:181], v[202:205], 0
	v_mfma_f32_16x16x32_bf16 v[18:21], v[182:185], v[206:209], v[18:21]
	s_setprio 2
	s_barrier
	v_mfma_f32_16x16x32_bf16 v[10:13], v[170:173], v[210:213], 0
	v_mfma_f32_16x16x32_bf16 v[10:13], v[174:177], v[214:217], v[10:13]
	v_mfma_f32_16x16x32_bf16 v[2:5], v[178:181], v[210:213], 0
	v_mfma_f32_16x16x32_bf16 v[2:5], v[182:185], v[214:217], v[2:5]
	s_setprio 0
	s_nop 0
	s_add_i32 s45, 0, 0x18000
	s_add_i32 s46, 0, 0x1c000
	ds_read_b128 v[154:157], v229 offset:32768
	ds_read_b128 v[158:161], v229 offset:33792
	ds_read_b128 v[162:165], v229 offset:34816
	ds_read_b128 v[166:169], v229 offset:35840
	ds_read_b128 v[170:173], v229 offset:49152
	ds_read_b128 v[174:177], v229 offset:50176
	ds_read_b128 v[178:181], v229 offset:51200
	ds_read_b128 v[182:185], v229 offset:52224
	s_add_u32 s24, s24, 0x40000
	s_addc_u32 s25, s25, 0
	s_mov_b32 m0, s29
	ds_read_b128 v[186:189], v152 offset:32768
	ds_read_b128 v[190:193], v152 offset:33792
	ds_read_b128 v[194:197], v152 offset:34816
	ds_read_b128 v[198:201], v152 offset:35840
	ds_read_b128 v[202:205], v152 offset:36864
	ds_read_b128 v[206:209], v152 offset:37888
	ds_read_b128 v[210:213], v152 offset:38912
	ds_read_b128 v[214:217], v152 offset:39936
	global_load_lds_dwordx4 v136, s[24:25]
	s_mov_b32 m0, s30
	s_nop 0
	global_load_lds_dwordx4 v132, s[24:25]
	s_waitcnt vmcnt(8)
	s_waitcnt lgkmcnt(0)
	s_barrier
	s_setprio 1
	v_mfma_f32_16x16x32_bf16 v[126:129], v[154:157], v[186:189], v[126:129]
	v_mfma_f32_16x16x32_bf16 v[126:129], v[158:161], v[190:193], v[126:129]
	v_mfma_f32_16x16x32_bf16 v[118:121], v[162:165], v[186:189], v[118:121]
	v_mfma_f32_16x16x32_bf16 v[118:121], v[166:169], v[190:193], v[118:121]
	v_mfma_f32_16x16x32_bf16 v[110:113], v[154:157], v[194:197], v[110:113]
	v_mfma_f32_16x16x32_bf16 v[110:113], v[158:161], v[198:201], v[110:113]
	v_mfma_f32_16x16x32_bf16 v[102:105], v[162:165], v[194:197], v[102:105]
	v_mfma_f32_16x16x32_bf16 v[102:105], v[166:169], v[198:201], v[102:105]
	v_mfma_f32_16x16x32_bf16 v[94:97], v[154:157], v[202:205], v[94:97]
	v_mfma_f32_16x16x32_bf16 v[94:97], v[158:161], v[206:209], v[94:97]
	v_mfma_f32_16x16x32_bf16 v[86:89], v[162:165], v[202:205], v[86:89]
	v_mfma_f32_16x16x32_bf16 v[86:89], v[166:169], v[206:209], v[86:89]
	v_mfma_f32_16x16x32_bf16 v[78:81], v[154:157], v[210:213], v[78:81]
	v_mfma_f32_16x16x32_bf16 v[78:81], v[158:161], v[214:217], v[78:81]
	v_mfma_f32_16x16x32_bf16 v[70:73], v[162:165], v[210:213], v[70:73]
	v_mfma_f32_16x16x32_bf16 v[70:73], v[166:169], v[214:217], v[70:73]
	v_mfma_f32_16x16x32_bf16 v[122:125], v[170:173], v[186:189], v[122:125]
	v_mfma_f32_16x16x32_bf16 v[122:125], v[174:177], v[190:193], v[122:125]
	v_mfma_f32_16x16x32_bf16 v[114:117], v[178:181], v[186:189], v[114:117]
	v_mfma_f32_16x16x32_bf16 v[114:117], v[182:185], v[190:193], v[114:117]
	v_mfma_f32_16x16x32_bf16 v[106:109], v[170:173], v[194:197], v[106:109]
	v_mfma_f32_16x16x32_bf16 v[106:109], v[174:177], v[198:201], v[106:109]
	v_mfma_f32_16x16x32_bf16 v[98:101], v[178:181], v[194:197], v[98:101]
	v_mfma_f32_16x16x32_bf16 v[98:101], v[182:185], v[198:201], v[98:101]
	v_mfma_f32_16x16x32_bf16 v[90:93], v[170:173], v[202:205], v[90:93]
	v_mfma_f32_16x16x32_bf16 v[90:93], v[174:177], v[206:209], v[90:93]
	v_mfma_f32_16x16x32_bf16 v[82:85], v[178:181], v[202:205], v[82:85]
	v_mfma_f32_16x16x32_bf16 v[82:85], v[182:185], v[206:209], v[82:85]
	s_setprio 2
	s_barrier
	v_mfma_f32_16x16x32_bf16 v[74:77], v[170:173], v[210:213], v[74:77]
	v_mfma_f32_16x16x32_bf16 v[74:77], v[174:177], v[214:217], v[74:77]
	v_mfma_f32_16x16x32_bf16 v[66:69], v[178:181], v[210:213], v[66:69]
	v_mfma_f32_16x16x32_bf16 v[66:69], v[182:185], v[214:217], v[66:69]
	s_setprio 0
	s_nop 0
	s_add_i32 s24, s45, s26
	s_mov_b32 m0, s24
	ds_read_b128 v[186:189], v152 offset:49152
	ds_read_b128 v[190:193], v152 offset:50176
	ds_read_b128 v[194:197], v152 offset:51200
	ds_read_b128 v[198:201], v152 offset:52224
	ds_read_b128 v[202:205], v152 offset:53248
	ds_read_b128 v[206:209], v152 offset:54272
	ds_read_b128 v[210:213], v152 offset:55296
	ds_read_b128 v[214:217], v152 offset:56320
	global_load_lds_dwordx4 v134, s[50:51]
	s_add_i32 m0, s24, 0x2000
	s_add_u32 s22, s22, 0x40080
	s_addc_u32 s23, s23, 0
	s_add_i32 s24, s46, s26
	global_load_lds_dwordx4 v130, s[50:51]
	s_mov_b32 m0, s24
	s_nop 0
	global_load_lds_dwordx4 v134, s[22:23]
	s_add_i32 m0, s24, 0x2000
	s_nop 0
	global_load_lds_dwordx4 v130, s[22:23]
	s_mov_b32 m0, s33
	s_nop 0
	global_load_lds_dwordx4 v136, s[52:53]
	s_mov_b32 m0, s34
	s_nop 0
	global_load_lds_dwordx4 v132, s[52:53]
	s_waitcnt vmcnt(8)
	s_waitcnt lgkmcnt(0)
	s_barrier
	s_setprio 1
	v_mfma_f32_16x16x32_bf16 v[62:65], v[154:157], v[186:189], v[62:65]
	v_mfma_f32_16x16x32_bf16 v[62:65], v[158:161], v[190:193], v[62:65]
	v_mfma_f32_16x16x32_bf16 v[54:57], v[162:165], v[186:189], v[54:57]
	v_mfma_f32_16x16x32_bf16 v[54:57], v[166:169], v[190:193], v[54:57]
	v_mfma_f32_16x16x32_bf16 v[46:49], v[154:157], v[194:197], v[46:49]
	v_mfma_f32_16x16x32_bf16 v[46:49], v[158:161], v[198:201], v[46:49]
	v_mfma_f32_16x16x32_bf16 v[38:41], v[162:165], v[194:197], v[38:41]
	v_mfma_f32_16x16x32_bf16 v[38:41], v[166:169], v[198:201], v[38:41]
	v_mfma_f32_16x16x32_bf16 v[30:33], v[154:157], v[202:205], v[30:33]
	v_mfma_f32_16x16x32_bf16 v[30:33], v[158:161], v[206:209], v[30:33]
	v_mfma_f32_16x16x32_bf16 v[22:25], v[162:165], v[202:205], v[22:25]
	v_mfma_f32_16x16x32_bf16 v[22:25], v[166:169], v[206:209], v[22:25]
	v_mfma_f32_16x16x32_bf16 v[14:17], v[154:157], v[210:213], v[14:17]
	v_mfma_f32_16x16x32_bf16 v[14:17], v[158:161], v[214:217], v[14:17]
	v_mfma_f32_16x16x32_bf16 v[6:9], v[162:165], v[210:213], v[6:9]
	v_mfma_f32_16x16x32_bf16 v[6:9], v[166:169], v[214:217], v[6:9]
	v_mfma_f32_16x16x32_bf16 v[58:61], v[170:173], v[186:189], v[58:61]
	v_mfma_f32_16x16x32_bf16 v[58:61], v[174:177], v[190:193], v[58:61]
	v_mfma_f32_16x16x32_bf16 v[50:53], v[178:181], v[186:189], v[50:53]
	v_mfma_f32_16x16x32_bf16 v[50:53], v[182:185], v[190:193], v[50:53]
	v_mfma_f32_16x16x32_bf16 v[42:45], v[170:173], v[194:197], v[42:45]
	v_mfma_f32_16x16x32_bf16 v[42:45], v[174:177], v[198:201], v[42:45]
	v_mfma_f32_16x16x32_bf16 v[34:37], v[178:181], v[194:197], v[34:37]
	v_mfma_f32_16x16x32_bf16 v[34:37], v[182:185], v[198:201], v[34:37]
	v_mfma_f32_16x16x32_bf16 v[26:29], v[170:173], v[202:205], v[26:29]
	v_mfma_f32_16x16x32_bf16 v[26:29], v[174:177], v[206:209], v[26:29]
	v_mfma_f32_16x16x32_bf16 v[18:21], v[178:181], v[202:205], v[18:21]
	v_mfma_f32_16x16x32_bf16 v[18:21], v[182:185], v[206:209], v[18:21]
	s_setprio 2
	s_barrier
	v_mfma_f32_16x16x32_bf16 v[10:13], v[170:173], v[210:213], v[10:13]
	v_mfma_f32_16x16x32_bf16 v[10:13], v[174:177], v[214:217], v[10:13]
	v_mfma_f32_16x16x32_bf16 v[2:5], v[178:181], v[210:213], v[2:5]
	v_mfma_f32_16x16x32_bf16 v[2:5], v[182:185], v[214:217], v[2:5]
	s_setprio 0
	s_nop 0
	s_add_i32 s44, s44, 2
	s_add_u32 s20, s20, 0x100
	s_addc_u32 s21, s21, 0
	s_cmp_gt_u32 s44, 13
	s_cbranch_scc1 .LBB0_948
	s_branch .LBB0_946
.LBB0_945:
	ds_read_b128 v[154:157], v229
	ds_read_b128 v[158:161], v229 offset:1024
	ds_read_b128 v[162:165], v229 offset:2048
	ds_read_b128 v[166:169], v229 offset:3072
	s_add_u32 s22, s18, s20
	ds_read_b128 v[170:173], v229 offset:16384
	ds_read_b128 v[174:177], v229 offset:17408
	ds_read_b128 v[178:181], v229 offset:18432
	ds_read_b128 v[182:185], v229 offset:19456
	s_addc_u32 s23, s19, s21
	s_add_u32 s22, s22, 0x100
	s_addc_u32 s23, s23, 0
	s_add_u32 s45, s42, s20
	s_addc_u32 s46, s43, s21
	s_cmpk_eq_i32 s20, 0x700
	s_cselect_b32 s25, s9, s23
	s_cselect_b32 s24, s39, s22
	s_cselect_b32 s23, s40, s46
	s_cselect_b32 s22, s41, s45
	s_add_u32 s48, s18, s20
	s_addc_u32 s49, s19, s21
	s_add_i32 m0, s27, 0xc000
	ds_read_b128 v[186:189], v152
	ds_read_b128 v[190:193], v152 offset:1024
	ds_read_b128 v[194:197], v152 offset:2048
	ds_read_b128 v[198:201], v152 offset:3072
	ds_read_b128 v[202:205], v152 offset:4096
	ds_read_b128 v[206:209], v152 offset:5120
	ds_read_b128 v[210:213], v152 offset:6144
	ds_read_b128 v[214:217], v152 offset:7168
	global_load_lds_dwordx4 v138, s[48:49]
	s_add_i32 m0, s27, 0xe000
	s_nop 0
	global_load_lds_dwordx4 v140, s[48:49]
	s_waitcnt vmcnt(8)
	s_waitcnt lgkmcnt(0)
	s_barrier
	s_setprio 1
	v_mfma_f32_16x16x32_bf16 v[126:129], v[154:157], v[186:189], v[126:129]
	v_mfma_f32_16x16x32_bf16 v[126:129], v[158:161], v[190:193], v[126:129]
	v_mfma_f32_16x16x32_bf16 v[118:121], v[162:165], v[186:189], v[118:121]
	v_mfma_f32_16x16x32_bf16 v[118:121], v[166:169], v[190:193], v[118:121]
	v_mfma_f32_16x16x32_bf16 v[110:113], v[154:157], v[194:197], v[110:113]
	v_mfma_f32_16x16x32_bf16 v[110:113], v[158:161], v[198:201], v[110:113]
	v_mfma_f32_16x16x32_bf16 v[102:105], v[162:165], v[194:197], v[102:105]
	v_mfma_f32_16x16x32_bf16 v[102:105], v[166:169], v[198:201], v[102:105]
	v_mfma_f32_16x16x32_bf16 v[94:97], v[154:157], v[202:205], v[94:97]
	v_mfma_f32_16x16x32_bf16 v[94:97], v[158:161], v[206:209], v[94:97]
	v_mfma_f32_16x16x32_bf16 v[86:89], v[162:165], v[202:205], v[86:89]
	v_mfma_f32_16x16x32_bf16 v[86:89], v[166:169], v[206:209], v[86:89]
	v_mfma_f32_16x16x32_bf16 v[78:81], v[154:157], v[210:213], v[78:81]
	v_mfma_f32_16x16x32_bf16 v[78:81], v[158:161], v[214:217], v[78:81]
	v_mfma_f32_16x16x32_bf16 v[70:73], v[162:165], v[210:213], v[70:73]
	v_mfma_f32_16x16x32_bf16 v[70:73], v[166:169], v[214:217], v[70:73]
	v_mfma_f32_16x16x32_bf16 v[122:125], v[170:173], v[186:189], v[122:125]
	v_mfma_f32_16x16x32_bf16 v[122:125], v[174:177], v[190:193], v[122:125]
	v_mfma_f32_16x16x32_bf16 v[114:117], v[178:181], v[186:189], v[114:117]
	v_mfma_f32_16x16x32_bf16 v[114:117], v[182:185], v[190:193], v[114:117]
	v_mfma_f32_16x16x32_bf16 v[106:109], v[170:173], v[194:197], v[106:109]
	v_mfma_f32_16x16x32_bf16 v[106:109], v[174:177], v[198:201], v[106:109]
	v_mfma_f32_16x16x32_bf16 v[98:101], v[178:181], v[194:197], v[98:101]
	v_mfma_f32_16x16x32_bf16 v[98:101], v[182:185], v[198:201], v[98:101]
	v_mfma_f32_16x16x32_bf16 v[90:93], v[170:173], v[202:205], v[90:93]
	v_mfma_f32_16x16x32_bf16 v[90:93], v[174:177], v[206:209], v[90:93]
	v_mfma_f32_16x16x32_bf16 v[82:85], v[178:181], v[202:205], v[82:85]
	v_mfma_f32_16x16x32_bf16 v[82:85], v[182:185], v[206:209], v[82:85]
	s_setprio 2
	s_barrier
	v_mfma_f32_16x16x32_bf16 v[74:77], v[170:173], v[210:213], v[74:77]
	v_mfma_f32_16x16x32_bf16 v[74:77], v[174:177], v[214:217], v[74:77]
	v_mfma_f32_16x16x32_bf16 v[66:69], v[178:181], v[210:213], v[66:69]
	v_mfma_f32_16x16x32_bf16 v[66:69], v[182:185], v[214:217], v[66:69]
	s_setprio 0
	s_nop 0
	s_add_i32 s45, s35, s26
	s_add_u32 s50, s22, 0x80
	s_addc_u32 s51, s23, 0
	s_add_u32 s52, s24, 0x80
	s_addc_u32 s53, s25, 0
	s_mov_b32 m0, s45
	ds_read_b128 v[186:189], v152 offset:16384
	ds_read_b128 v[190:193], v152 offset:17408
	ds_read_b128 v[194:197], v152 offset:18432
	ds_read_b128 v[198:201], v152 offset:19456
	ds_read_b128 v[202:205], v152 offset:20480
	ds_read_b128 v[206:209], v152 offset:21504
	ds_read_b128 v[210:213], v152 offset:22528
	ds_read_b128 v[214:217], v152 offset:23552
	global_load_lds_dwordx4 v134, s[22:23]
	s_add_i32 m0, s45, 0x2000
	s_add_u32 s46, s22, 0x40000
	s_addc_u32 s47, s23, 0
	s_add_i32 s45, s36, s26
	global_load_lds_dwordx4 v130, s[22:23]
	s_mov_b32 m0, s45
	s_nop 0
	global_load_lds_dwordx4 v134, s[46:47]
	s_add_i32 m0, s45, 0x2000
	s_nop 0
	global_load_lds_dwordx4 v130, s[46:47]
	s_mov_b32 m0, s27
	s_nop 0
	global_load_lds_dwordx4 v136, s[24:25]
	s_mov_b32 m0, s28
	s_nop 0
	global_load_lds_dwordx4 v132, s[24:25]
	s_waitcnt vmcnt(8)
	s_waitcnt lgkmcnt(0)
	s_barrier
	s_setprio 1
	v_mfma_f32_16x16x32_bf16 v[62:65], v[154:157], v[186:189], v[62:65]
	v_mfma_f32_16x16x32_bf16 v[62:65], v[158:161], v[190:193], v[62:65]
	v_mfma_f32_16x16x32_bf16 v[54:57], v[162:165], v[186:189], v[54:57]
	v_mfma_f32_16x16x32_bf16 v[54:57], v[166:169], v[190:193], v[54:57]
	v_mfma_f32_16x16x32_bf16 v[46:49], v[154:157], v[194:197], v[46:49]
	v_mfma_f32_16x16x32_bf16 v[46:49], v[158:161], v[198:201], v[46:49]
	v_mfma_f32_16x16x32_bf16 v[38:41], v[162:165], v[194:197], v[38:41]
	v_mfma_f32_16x16x32_bf16 v[38:41], v[166:169], v[198:201], v[38:41]
	v_mfma_f32_16x16x32_bf16 v[30:33], v[154:157], v[202:205], v[30:33]
	v_mfma_f32_16x16x32_bf16 v[30:33], v[158:161], v[206:209], v[30:33]
	v_mfma_f32_16x16x32_bf16 v[22:25], v[162:165], v[202:205], v[22:25]
	v_mfma_f32_16x16x32_bf16 v[22:25], v[166:169], v[206:209], v[22:25]
	v_mfma_f32_16x16x32_bf16 v[14:17], v[154:157], v[210:213], v[14:17]
	v_mfma_f32_16x16x32_bf16 v[14:17], v[158:161], v[214:217], v[14:17]
	v_mfma_f32_16x16x32_bf16 v[6:9], v[162:165], v[210:213], v[6:9]
	v_mfma_f32_16x16x32_bf16 v[6:9], v[166:169], v[214:217], v[6:9]
	v_mfma_f32_16x16x32_bf16 v[58:61], v[170:173], v[186:189], v[58:61]
	v_mfma_f32_16x16x32_bf16 v[58:61], v[174:177], v[190:193], v[58:61]
	v_mfma_f32_16x16x32_bf16 v[50:53], v[178:181], v[186:189], v[50:53]
	v_mfma_f32_16x16x32_bf16 v[50:53], v[182:185], v[190:193], v[50:53]
	v_mfma_f32_16x16x32_bf16 v[42:45], v[170:173], v[194:197], v[42:45]
	v_mfma_f32_16x16x32_bf16 v[42:45], v[174:177], v[198:201], v[42:45]
	v_mfma_f32_16x16x32_bf16 v[34:37], v[178:181], v[194:197], v[34:37]
	v_mfma_f32_16x16x32_bf16 v[34:37], v[182:185], v[198:201], v[34:37]
	v_mfma_f32_16x16x32_bf16 v[26:29], v[170:173], v[202:205], v[26:29]
	v_mfma_f32_16x16x32_bf16 v[26:29], v[174:177], v[206:209], v[26:29]
	v_mfma_f32_16x16x32_bf16 v[18:21], v[178:181], v[202:205], v[18:21]
	v_mfma_f32_16x16x32_bf16 v[18:21], v[182:185], v[206:209], v[18:21]
	s_setprio 2
	s_barrier
	v_mfma_f32_16x16x32_bf16 v[10:13], v[170:173], v[210:213], v[10:13]
	v_mfma_f32_16x16x32_bf16 v[10:13], v[174:177], v[214:217], v[10:13]
	v_mfma_f32_16x16x32_bf16 v[2:5], v[178:181], v[210:213], v[2:5]
	v_mfma_f32_16x16x32_bf16 v[2:5], v[182:185], v[214:217], v[2:5]
	s_setprio 0
	s_nop 0
	s_add_i32 s45, 0, 0x18000
	s_add_i32 s46, 0, 0x1c000
	ds_read_b128 v[154:157], v229 offset:32768
	ds_read_b128 v[158:161], v229 offset:33792
	ds_read_b128 v[162:165], v229 offset:34816
	ds_read_b128 v[166:169], v229 offset:35840
	ds_read_b128 v[170:173], v229 offset:49152
	ds_read_b128 v[174:177], v229 offset:50176
	ds_read_b128 v[178:181], v229 offset:51200
	ds_read_b128 v[182:185], v229 offset:52224
	s_add_u32 s24, s24, 0x40000
	s_addc_u32 s25, s25, 0
	s_mov_b32 m0, s29
	ds_read_b128 v[186:189], v152 offset:32768
	ds_read_b128 v[190:193], v152 offset:33792
	ds_read_b128 v[194:197], v152 offset:34816
	ds_read_b128 v[198:201], v152 offset:35840
	ds_read_b128 v[202:205], v152 offset:36864
	ds_read_b128 v[206:209], v152 offset:37888
	ds_read_b128 v[210:213], v152 offset:38912
	ds_read_b128 v[214:217], v152 offset:39936
	global_load_lds_dwordx4 v136, s[24:25]
	s_mov_b32 m0, s30
	s_nop 0
	global_load_lds_dwordx4 v132, s[24:25]
	s_waitcnt vmcnt(8)
	s_waitcnt lgkmcnt(0)
	s_barrier
	s_setprio 1
	v_mfma_f32_16x16x32_bf16 v[126:129], v[154:157], v[186:189], v[126:129]
	v_mfma_f32_16x16x32_bf16 v[126:129], v[158:161], v[190:193], v[126:129]
	v_mfma_f32_16x16x32_bf16 v[118:121], v[162:165], v[186:189], v[118:121]
	v_mfma_f32_16x16x32_bf16 v[118:121], v[166:169], v[190:193], v[118:121]
	v_mfma_f32_16x16x32_bf16 v[110:113], v[154:157], v[194:197], v[110:113]
	v_mfma_f32_16x16x32_bf16 v[110:113], v[158:161], v[198:201], v[110:113]
	v_mfma_f32_16x16x32_bf16 v[102:105], v[162:165], v[194:197], v[102:105]
	v_mfma_f32_16x16x32_bf16 v[102:105], v[166:169], v[198:201], v[102:105]
	v_mfma_f32_16x16x32_bf16 v[94:97], v[154:157], v[202:205], v[94:97]
	v_mfma_f32_16x16x32_bf16 v[94:97], v[158:161], v[206:209], v[94:97]
	v_mfma_f32_16x16x32_bf16 v[86:89], v[162:165], v[202:205], v[86:89]
	v_mfma_f32_16x16x32_bf16 v[86:89], v[166:169], v[206:209], v[86:89]
	v_mfma_f32_16x16x32_bf16 v[78:81], v[154:157], v[210:213], v[78:81]
	v_mfma_f32_16x16x32_bf16 v[78:81], v[158:161], v[214:217], v[78:81]
	v_mfma_f32_16x16x32_bf16 v[70:73], v[162:165], v[210:213], v[70:73]
	v_mfma_f32_16x16x32_bf16 v[70:73], v[166:169], v[214:217], v[70:73]
	v_mfma_f32_16x16x32_bf16 v[122:125], v[170:173], v[186:189], v[122:125]
	v_mfma_f32_16x16x32_bf16 v[122:125], v[174:177], v[190:193], v[122:125]
	v_mfma_f32_16x16x32_bf16 v[114:117], v[178:181], v[186:189], v[114:117]
	v_mfma_f32_16x16x32_bf16 v[114:117], v[182:185], v[190:193], v[114:117]
	v_mfma_f32_16x16x32_bf16 v[106:109], v[170:173], v[194:197], v[106:109]
	v_mfma_f32_16x16x32_bf16 v[106:109], v[174:177], v[198:201], v[106:109]
	v_mfma_f32_16x16x32_bf16 v[98:101], v[178:181], v[194:197], v[98:101]
	v_mfma_f32_16x16x32_bf16 v[98:101], v[182:185], v[198:201], v[98:101]
	v_mfma_f32_16x16x32_bf16 v[90:93], v[170:173], v[202:205], v[90:93]
	v_mfma_f32_16x16x32_bf16 v[90:93], v[174:177], v[206:209], v[90:93]
	v_mfma_f32_16x16x32_bf16 v[82:85], v[178:181], v[202:205], v[82:85]
	v_mfma_f32_16x16x32_bf16 v[82:85], v[182:185], v[206:209], v[82:85]
	s_setprio 2
	s_barrier
	v_mfma_f32_16x16x32_bf16 v[74:77], v[170:173], v[210:213], v[74:77]
	v_mfma_f32_16x16x32_bf16 v[74:77], v[174:177], v[214:217], v[74:77]
	v_mfma_f32_16x16x32_bf16 v[66:69], v[178:181], v[210:213], v[66:69]
	v_mfma_f32_16x16x32_bf16 v[66:69], v[182:185], v[214:217], v[66:69]
	s_setprio 0
	s_nop 0
	s_add_i32 s24, s45, s26
	s_mov_b32 m0, s24
	ds_read_b128 v[186:189], v152 offset:49152
	ds_read_b128 v[190:193], v152 offset:50176
	ds_read_b128 v[194:197], v152 offset:51200
	ds_read_b128 v[198:201], v152 offset:52224
	ds_read_b128 v[202:205], v152 offset:53248
	ds_read_b128 v[206:209], v152 offset:54272
	ds_read_b128 v[210:213], v152 offset:55296
	ds_read_b128 v[214:217], v152 offset:56320
	global_load_lds_dwordx4 v134, s[50:51]
	s_add_i32 m0, s24, 0x2000
	s_add_u32 s22, s22, 0x40080
	s_addc_u32 s23, s23, 0
	s_add_i32 s24, s46, s26
	global_load_lds_dwordx4 v130, s[50:51]
	s_mov_b32 m0, s24
	s_nop 0
	global_load_lds_dwordx4 v134, s[22:23]
	s_add_i32 m0, s24, 0x2000
	s_nop 0
	global_load_lds_dwordx4 v130, s[22:23]
	s_mov_b32 m0, s33
	s_nop 0
	global_load_lds_dwordx4 v136, s[52:53]
	s_mov_b32 m0, s34
	s_nop 0
	global_load_lds_dwordx4 v132, s[52:53]
	s_waitcnt vmcnt(8)
	s_waitcnt lgkmcnt(0)
	s_barrier
	s_setprio 1
	v_mfma_f32_16x16x32_bf16 v[62:65], v[154:157], v[186:189], v[62:65]
	v_mfma_f32_16x16x32_bf16 v[62:65], v[158:161], v[190:193], v[62:65]
	v_mfma_f32_16x16x32_bf16 v[54:57], v[162:165], v[186:189], v[54:57]
	v_mfma_f32_16x16x32_bf16 v[54:57], v[166:169], v[190:193], v[54:57]
	v_mfma_f32_16x16x32_bf16 v[46:49], v[154:157], v[194:197], v[46:49]
	v_mfma_f32_16x16x32_bf16 v[46:49], v[158:161], v[198:201], v[46:49]
	v_mfma_f32_16x16x32_bf16 v[38:41], v[162:165], v[194:197], v[38:41]
	v_mfma_f32_16x16x32_bf16 v[38:41], v[166:169], v[198:201], v[38:41]
	v_mfma_f32_16x16x32_bf16 v[30:33], v[154:157], v[202:205], v[30:33]
	v_mfma_f32_16x16x32_bf16 v[30:33], v[158:161], v[206:209], v[30:33]
	v_mfma_f32_16x16x32_bf16 v[22:25], v[162:165], v[202:205], v[22:25]
	v_mfma_f32_16x16x32_bf16 v[22:25], v[166:169], v[206:209], v[22:25]
	v_mfma_f32_16x16x32_bf16 v[14:17], v[154:157], v[210:213], v[14:17]
	v_mfma_f32_16x16x32_bf16 v[14:17], v[158:161], v[214:217], v[14:17]
	v_mfma_f32_16x16x32_bf16 v[6:9], v[162:165], v[210:213], v[6:9]
	v_mfma_f32_16x16x32_bf16 v[6:9], v[166:169], v[214:217], v[6:9]
	v_mfma_f32_16x16x32_bf16 v[58:61], v[170:173], v[186:189], v[58:61]
	v_mfma_f32_16x16x32_bf16 v[58:61], v[174:177], v[190:193], v[58:61]
	v_mfma_f32_16x16x32_bf16 v[50:53], v[178:181], v[186:189], v[50:53]
	v_mfma_f32_16x16x32_bf16 v[50:53], v[182:185], v[190:193], v[50:53]
	v_mfma_f32_16x16x32_bf16 v[42:45], v[170:173], v[194:197], v[42:45]
	v_mfma_f32_16x16x32_bf16 v[42:45], v[174:177], v[198:201], v[42:45]
	v_mfma_f32_16x16x32_bf16 v[34:37], v[178:181], v[194:197], v[34:37]
	v_mfma_f32_16x16x32_bf16 v[34:37], v[182:185], v[198:201], v[34:37]
	v_mfma_f32_16x16x32_bf16 v[26:29], v[170:173], v[202:205], v[26:29]
	v_mfma_f32_16x16x32_bf16 v[26:29], v[174:177], v[206:209], v[26:29]
	v_mfma_f32_16x16x32_bf16 v[18:21], v[178:181], v[202:205], v[18:21]
	v_mfma_f32_16x16x32_bf16 v[18:21], v[182:185], v[206:209], v[18:21]
	s_setprio 2
	s_barrier
	v_mfma_f32_16x16x32_bf16 v[10:13], v[170:173], v[210:213], v[10:13]
	v_mfma_f32_16x16x32_bf16 v[10:13], v[174:177], v[214:217], v[10:13]
	v_mfma_f32_16x16x32_bf16 v[2:5], v[178:181], v[210:213], v[2:5]
	v_mfma_f32_16x16x32_bf16 v[2:5], v[182:185], v[214:217], v[2:5]
	s_setprio 0
	s_nop 0
	s_add_i32 s44, s44, 2
	s_add_u32 s20, s20, 0x100
	s_addc_u32 s21, s21, 0
	s_cmp_gt_u32 s44, 13
	s_cbranch_scc1 .LBB0_948

.LBB0_1017:
	v_lshl_add_u64 v[14:15], s[14:15], 0, v[130:131]
	v_lshl_add_u64 v[16:17], s[14:15], 0, v[134:135]
	s_add_i32 m0, s50, 0x18000
	v_lshl_add_u64 v[14:15], v[14:15], 0, s[24:25]
	s_waitcnt vmcnt(2)
	s_barrier
	global_load_lds_dwordx4 v[14:15], off
	v_lshl_add_u64 v[14:15], v[16:17], 0, s[24:25]
	s_add_i32 m0, s50, 0x1a000
	s_add_i32 s54, s50, 0x8000
	global_load_lds_dwordx4 v[14:15], off
	v_lshl_add_u64 v[4:5], v[4:5], 0, s[24:25]
	s_mov_b32 m0, s54
	s_add_i32 s55, s50, 0xa000
	global_load_lds_dwordx4 v[4:5], off
	v_lshl_add_u64 v[2:3], v[2:3], 0, s[24:25]
	s_mov_b32 m0, s55
	v_and_b32_e32 v212, 15, v211
	global_load_lds_dwordx4 v[2:3], off
	s_add_i32 m0, s50, 0x1c000
	v_lshl_add_u64 v[2:3], s[18:19], 0, v[130:131]
	global_load_lds_dwordx4 v[2:3], off
	v_lshl_add_u64 v[2:3], s[18:19], 0, v[134:135]
	s_add_i32 m0, s50, 0x1e000
	v_and_b32_e32 v18, 48, v211
	global_load_lds_dwordx4 v[2:3], off
	v_lshlrev_b32_e32 v19, 2, v211
	s_and_b32 s38, s34, 3
	s_lshl_b32 s4, s35, 13
	v_lshl_or_b32 v18, v212, 6, v18
	v_and_b32_e32 v19, 32, v19
	v_bitop3_b32 v20, v18, s4, v19 bitop3:0xde
	s_lshl_b32 s4, s38, 12
	s_add_u32 s56, s42, s3
	s_addc_u32 s57, s43, s2
	v_bitop3_b32 v140, v18, s4, v19 bitop3:0xde
	s_add_u32 s4, s44, s3
	v_lshrrev_b32_e32 v3, 1, v11
	v_mul_lo_u32 v2, v10, s46
	s_addc_u32 s5, s45, s2
	v_mad_u64_u32 v[2:3], s[2:3], v3, s47, v[2:3]
	v_or_b32_e32 v2, v2, v12
	v_add_lshl_u32 v2, v2, v13, 1
	v_mov_b32_e32 v3, v131
	v_lshl_add_u64 v[136:137], s[4:5], 0, v[2:3]
	v_lshrrev_b32_e32 v3, 1, v6
	v_mul_lo_u32 v2, v7, s46
	v_mad_u64_u32 v[2:3], s[2:3], v3, s47, v[2:3]
	v_or_b32_e32 v2, v2, v8
	s_waitcnt vmcnt(6)
	v_add_lshl_u32 v2, v2, v9, 1
	v_mov_b32_e32 v3, v131
	v_lshl_add_u64 v[138:139], s[4:5], 0, v[2:3]
	v_mov_b32_e32 v2, 0
	v_lshl_or_b32 v210, s35, 6, v212
	s_mov_b32 s58, -2
	v_add_u32_e32 v141, 0, v20
	s_mov_b64 s[2:3], s[22:23]
	s_barrier
	s_add_u32 s4, s70, s56
	s_addc_u32 s5, s71, s57
	s_add_u32 s59, s70, s2
	s_addc_u32 s60, s71, s3
	s_add_i32 s61, 0, 0x10000
	s_cmp_eq_u32 s58, 40
	s_cselect_b32 s31, s1, s5
	s_cselect_b32 s30, s0, s4
	s_cselect_b32 s5, s15, s60
	s_cselect_b32 s4, s14, s59
	s_add_i32 s59, 0, 0x14000
	v_add_u32_e32 v154, s61, v140
	v_add_u32_e32 v170, s59, v140
	ds_read_b128 v[142:145], v154
	ds_read_b128 v[146:149], v154 offset:1024
	ds_read_b128 v[150:153], v154 offset:2048
	ds_read_b128 v[154:157], v154 offset:3072
	ds_read_b128 v[158:161], v170
	ds_read_b128 v[162:165], v170 offset:1024
	ds_read_b128 v[166:169], v170 offset:2048
	ds_read_b128 v[170:173], v170 offset:3072
	v_lshl_add_u64 v[214:215], s[70:71], 0, v[136:137]
	s_add_i32 m0, s50, 0xc000
	ds_read_b128 v[174:177], v141
	ds_read_b128 v[178:181], v141 offset:1024
	ds_read_b128 v[182:185], v141 offset:2048
	ds_read_b128 v[186:189], v141 offset:3072
	ds_read_b128 v[190:193], v141 offset:4096
	ds_read_b128 v[194:197], v141 offset:5120
	ds_read_b128 v[198:201], v141 offset:6144
	ds_read_b128 v[202:205], v141 offset:7168
	global_load_lds_dwordx4 v[214:215], off
	v_lshl_add_u64 v[214:215], s[70:71], 0, v[138:139]
	s_add_i32 m0, s50, 0xe000
	s_nop 0
	global_load_lds_dwordx4 v[214:215], off
	s_waitcnt vmcnt(8)
	s_waitcnt lgkmcnt(0)
	s_barrier
	s_setprio 1
	v_mfma_f32_16x16x32_bf16 v[126:129], v[142:145], v[174:177], 0
	v_mfma_f32_16x16x32_bf16 v[126:129], v[146:149], v[178:181], v[126:129]
	v_mfma_f32_16x16x32_bf16 v[122:125], v[150:153], v[174:177], 0
	v_mfma_f32_16x16x32_bf16 v[122:125], v[154:157], v[178:181], v[122:125]
	v_mfma_f32_16x16x32_bf16 v[110:113], v[142:145], v[182:185], 0
	v_mfma_f32_16x16x32_bf16 v[110:113], v[146:149], v[186:189], v[110:113]
	v_mfma_f32_16x16x32_bf16 v[106:109], v[150:153], v[182:185], 0
	v_mfma_f32_16x16x32_bf16 v[106:109], v[154:157], v[186:189], v[106:109]
	v_mfma_f32_16x16x32_bf16 v[94:97], v[142:145], v[190:193], 0
	v_mfma_f32_16x16x32_bf16 v[94:97], v[146:149], v[194:197], v[94:97]
	v_mfma_f32_16x16x32_bf16 v[90:93], v[150:153], v[190:193], 0
	v_mfma_f32_16x16x32_bf16 v[90:93], v[154:157], v[194:197], v[90:93]
	v_mfma_f32_16x16x32_bf16 v[78:81], v[142:145], v[198:201], 0
	v_mfma_f32_16x16x32_bf16 v[78:81], v[146:149], v[202:205], v[78:81]
	v_mfma_f32_16x16x32_bf16 v[74:77], v[150:153], v[198:201], 0
	v_mfma_f32_16x16x32_bf16 v[74:77], v[154:157], v[202:205], v[74:77]
	v_mfma_f32_16x16x32_bf16 v[118:121], v[158:161], v[174:177], 0
	v_mfma_f32_16x16x32_bf16 v[118:121], v[162:165], v[178:181], v[118:121]
	v_mfma_f32_16x16x32_bf16 v[114:117], v[166:169], v[174:177], 0
	v_mfma_f32_16x16x32_bf16 v[114:117], v[170:173], v[178:181], v[114:117]
	v_mfma_f32_16x16x32_bf16 v[102:105], v[158:161], v[182:185], 0
	v_mfma_f32_16x16x32_bf16 v[102:105], v[162:165], v[186:189], v[102:105]
	v_mfma_f32_16x16x32_bf16 v[98:101], v[166:169], v[182:185], 0
	v_mfma_f32_16x16x32_bf16 v[98:101], v[170:173], v[186:189], v[98:101]
	v_mfma_f32_16x16x32_bf16 v[86:89], v[158:161], v[190:193], 0
	v_mfma_f32_16x16x32_bf16 v[86:89], v[162:165], v[194:197], v[86:89]
	v_mfma_f32_16x16x32_bf16 v[82:85], v[166:169], v[190:193], 0
	v_mfma_f32_16x16x32_bf16 v[82:85], v[170:173], v[194:197], v[82:85]
	s_setprio 2
	s_barrier
	v_mfma_f32_16x16x32_bf16 v[70:73], v[158:161], v[198:201], 0
	v_mfma_f32_16x16x32_bf16 v[70:73], v[162:165], v[202:205], v[70:73]
	v_mfma_f32_16x16x32_bf16 v[66:69], v[166:169], v[198:201], 0
	v_mfma_f32_16x16x32_bf16 v[66:69], v[170:173], v[202:205], v[66:69]
	s_setprio 0
	s_nop 0
	s_add_i32 s60, s61, s39
	v_lshl_add_u64 v[214:215], s[4:5], 0, v[130:131]
	s_mov_b32 m0, s60
	ds_read_b128 v[174:177], v141 offset:16384
	ds_read_b128 v[178:181], v141 offset:17408
	ds_read_b128 v[182:185], v141 offset:18432
	ds_read_b128 v[186:189], v141 offset:19456
	ds_read_b128 v[190:193], v141 offset:20480
	ds_read_b128 v[194:197], v141 offset:21504
	ds_read_b128 v[198:201], v141 offset:22528
	ds_read_b128 v[202:205], v141 offset:23552
	global_load_lds_dwordx4 v[214:215], off
	s_add_i32 m0, s60, 0x2000
	s_add_u32 s60, s4, 0xb0000
	v_lshl_add_u64 v[216:217], s[4:5], 0, v[134:135]
	s_addc_u32 s61, s5, 0
	s_add_i32 s59, s59, s39
	global_load_lds_dwordx4 v[216:217], off
	v_lshl_add_u64 v[218:219], s[60:61], 0, v[130:131]
	s_mov_b32 m0, s59
	v_lshl_add_u64 v[220:221], s[30:31], 0, v[134:135]
	global_load_lds_dwordx4 v[218:219], off
	v_lshl_add_u64 v[218:219], s[60:61], 0, v[134:135]
	s_add_i32 m0, s59, 0x2000
	s_nop 0
	global_load_lds_dwordx4 v[218:219], off
	v_lshl_add_u64 v[218:219], s[30:31], 0, v[130:131]
	s_mov_b32 m0, s50
	s_nop 0
	global_load_lds_dwordx4 v[218:219], off
	s_mov_b32 m0, s51
	s_nop 0
	global_load_lds_dwordx4 v[220:221], off
	s_waitcnt vmcnt(8)
	s_waitcnt lgkmcnt(0)
	s_barrier
	s_setprio 1
	v_mfma_f32_16x16x32_bf16 v[62:65], v[142:145], v[174:177], 0
	v_mfma_f32_16x16x32_bf16 v[62:65], v[146:149], v[178:181], v[62:65]
	v_mfma_f32_16x16x32_bf16 v[58:61], v[150:153], v[174:177], 0
	v_mfma_f32_16x16x32_bf16 v[58:61], v[154:157], v[178:181], v[58:61]
	v_mfma_f32_16x16x32_bf16 v[46:49], v[142:145], v[182:185], 0
	v_mfma_f32_16x16x32_bf16 v[46:49], v[146:149], v[186:189], v[46:49]
	v_mfma_f32_16x16x32_bf16 v[42:45], v[150:153], v[182:185], 0
	v_mfma_f32_16x16x32_bf16 v[42:45], v[154:157], v[186:189], v[42:45]
	v_mfma_f32_16x16x32_bf16 v[30:33], v[142:145], v[190:193], 0
	v_mfma_f32_16x16x32_bf16 v[30:33], v[146:149], v[194:197], v[30:33]
	v_mfma_f32_16x16x32_bf16 v[26:29], v[150:153], v[190:193], 0
	v_mfma_f32_16x16x32_bf16 v[26:29], v[154:157], v[194:197], v[26:29]
	v_mfma_f32_16x16x32_bf16 v[14:17], v[142:145], v[198:201], 0
	v_mfma_f32_16x16x32_bf16 v[14:17], v[146:149], v[202:205], v[14:17]
	v_mfma_f32_16x16x32_bf16 v[10:13], v[150:153], v[198:201], 0
	v_mfma_f32_16x16x32_bf16 v[10:13], v[154:157], v[202:205], v[10:13]
	v_mfma_f32_16x16x32_bf16 v[54:57], v[158:161], v[174:177], 0
	v_mfma_f32_16x16x32_bf16 v[54:57], v[162:165], v[178:181], v[54:57]
	v_mfma_f32_16x16x32_bf16 v[50:53], v[166:169], v[174:177], 0
	v_mfma_f32_16x16x32_bf16 v[50:53], v[170:173], v[178:181], v[50:53]
	v_mfma_f32_16x16x32_bf16 v[38:41], v[158:161], v[182:185], 0
	v_mfma_f32_16x16x32_bf16 v[38:41], v[162:165], v[186:189], v[38:41]
	v_mfma_f32_16x16x32_bf16 v[34:37], v[166:169], v[182:185], 0
	v_mfma_f32_16x16x32_bf16 v[34:37], v[170:173], v[186:189], v[34:37]
	v_mfma_f32_16x16x32_bf16 v[22:25], v[158:161], v[190:193], 0
	v_mfma_f32_16x16x32_bf16 v[22:25], v[162:165], v[194:197], v[22:25]
	v_mfma_f32_16x16x32_bf16 v[18:21], v[166:169], v[190:193], 0
	v_mfma_f32_16x16x32_bf16 v[18:21], v[170:173], v[194:197], v[18:21]
	s_setprio 2
	s_barrier
	v_mfma_f32_16x16x32_bf16 v[6:9], v[158:161], v[198:201], 0
	v_mfma_f32_16x16x32_bf16 v[6:9], v[162:165], v[202:205], v[6:9]
	v_mfma_f32_16x16x32_bf16 v[2:5], v[166:169], v[198:201], 0
	v_mfma_f32_16x16x32_bf16 v[2:5], v[170:173], v[202:205], v[2:5]
	s_setprio 0
	s_nop 0
	s_add_i32 s59, 0, 0x18000
	s_add_i32 s60, 0, 0x1c000
	v_add_u32_e32 v154, s59, v140
	v_add_u32_e32 v170, s60, v140
	ds_read_b128 v[142:145], v154
	ds_read_b128 v[146:149], v154 offset:1024
	ds_read_b128 v[150:153], v154 offset:2048
	ds_read_b128 v[154:157], v154 offset:3072
	ds_read_b128 v[158:161], v170
	ds_read_b128 v[162:165], v170 offset:1024
	ds_read_b128 v[166:169], v170 offset:2048
	ds_read_b128 v[170:173], v170 offset:3072
	s_add_u32 s30, s30, 0xb0000
	s_addc_u32 s31, s31, 0
	s_mov_b32 m0, s52
	v_lshl_add_u64 v[222:223], s[30:31], 0, v[130:131]
	ds_read_b128 v[174:177], v141 offset:32768
	ds_read_b128 v[178:181], v141 offset:33792
	ds_read_b128 v[182:185], v141 offset:34816
	ds_read_b128 v[186:189], v141 offset:35840
	ds_read_b128 v[190:193], v141 offset:36864
	ds_read_b128 v[194:197], v141 offset:37888
	ds_read_b128 v[198:201], v141 offset:38912
	ds_read_b128 v[202:205], v141 offset:39936
	global_load_lds_dwordx4 v[222:223], off
	v_lshl_add_u64 v[222:223], s[30:31], 0, v[134:135]
	s_mov_b32 m0, s53
	s_nop 0
	global_load_lds_dwordx4 v[222:223], off
	s_waitcnt vmcnt(8)
	s_waitcnt lgkmcnt(0)
	s_barrier
	s_setprio 1
	v_mfma_f32_16x16x32_bf16 v[126:129], v[142:145], v[174:177], v[126:129]
	v_mfma_f32_16x16x32_bf16 v[126:129], v[146:149], v[178:181], v[126:129]
	v_mfma_f32_16x16x32_bf16 v[122:125], v[150:153], v[174:177], v[122:125]
	v_mfma_f32_16x16x32_bf16 v[122:125], v[154:157], v[178:181], v[122:125]
	v_mfma_f32_16x16x32_bf16 v[110:113], v[142:145], v[182:185], v[110:113]
	v_mfma_f32_16x16x32_bf16 v[110:113], v[146:149], v[186:189], v[110:113]
	v_mfma_f32_16x16x32_bf16 v[106:109], v[150:153], v[182:185], v[106:109]
	v_mfma_f32_16x16x32_bf16 v[106:109], v[154:157], v[186:189], v[106:109]
	v_mfma_f32_16x16x32_bf16 v[94:97], v[142:145], v[190:193], v[94:97]
	v_mfma_f32_16x16x32_bf16 v[94:97], v[146:149], v[194:197], v[94:97]
	v_mfma_f32_16x16x32_bf16 v[90:93], v[150:153], v[190:193], v[90:93]
	v_mfma_f32_16x16x32_bf16 v[90:93], v[154:157], v[194:197], v[90:93]
	v_mfma_f32_16x16x32_bf16 v[78:81], v[142:145], v[198:201], v[78:81]
	v_mfma_f32_16x16x32_bf16 v[78:81], v[146:149], v[202:205], v[78:81]
	v_mfma_f32_16x16x32_bf16 v[74:77], v[150:153], v[198:201], v[74:77]
	v_mfma_f32_16x16x32_bf16 v[74:77], v[154:157], v[202:205], v[74:77]
	v_mfma_f32_16x16x32_bf16 v[118:121], v[158:161], v[174:177], v[118:121]
	v_mfma_f32_16x16x32_bf16 v[118:121], v[162:165], v[178:181], v[118:121]
	v_mfma_f32_16x16x32_bf16 v[114:117], v[166:169], v[174:177], v[114:117]
	v_mfma_f32_16x16x32_bf16 v[114:117], v[170:173], v[178:181], v[114:117]
	v_mfma_f32_16x16x32_bf16 v[102:105], v[158:161], v[182:185], v[102:105]
	v_mfma_f32_16x16x32_bf16 v[102:105], v[162:165], v[186:189], v[102:105]
	v_mfma_f32_16x16x32_bf16 v[98:101], v[166:169], v[182:185], v[98:101]
	v_mfma_f32_16x16x32_bf16 v[98:101], v[170:173], v[186:189], v[98:101]
	v_mfma_f32_16x16x32_bf16 v[86:89], v[158:161], v[190:193], v[86:89]
	v_mfma_f32_16x16x32_bf16 v[86:89], v[162:165], v[194:197], v[86:89]
	v_mfma_f32_16x16x32_bf16 v[82:85], v[166:169], v[190:193], v[82:85]
	v_mfma_f32_16x16x32_bf16 v[82:85], v[170:173], v[194:197], v[82:85]
	s_setprio 2
	s_barrier
	v_mfma_f32_16x16x32_bf16 v[70:73], v[158:161], v[198:201], v[70:73]
	v_mfma_f32_16x16x32_bf16 v[70:73], v[162:165], v[202:205], v[70:73]
	v_mfma_f32_16x16x32_bf16 v[66:69], v[166:169], v[198:201], v[66:69]
	v_mfma_f32_16x16x32_bf16 v[66:69], v[170:173], v[202:205], v[66:69]
	s_setprio 0
	s_nop 0
	s_add_i32 s30, s59, s39
	v_lshl_add_u64 v[214:215], v[214:215], 0, s[24:25]
	s_mov_b32 m0, s30
	ds_read_b128 v[174:177], v141 offset:49152
	ds_read_b128 v[178:181], v141 offset:50176
	ds_read_b128 v[182:185], v141 offset:51200
	ds_read_b128 v[186:189], v141 offset:52224
	ds_read_b128 v[190:193], v141 offset:53248
	ds_read_b128 v[194:197], v141 offset:54272
	ds_read_b128 v[198:201], v141 offset:55296
	ds_read_b128 v[202:205], v141 offset:56320
	global_load_lds_dwordx4 v[214:215], off
	s_add_i32 m0, s30, 0x2000
	s_add_u32 s4, s4, 0xb0080
	v_lshl_add_u64 v[214:215], v[216:217], 0, s[24:25]
	s_addc_u32 s5, s5, 0
	s_add_i32 s30, s60, s39
	global_load_lds_dwordx4 v[214:215], off
	v_lshl_add_u64 v[214:215], s[4:5], 0, v[130:131]
	s_mov_b32 m0, s30
	s_nop 0
	global_load_lds_dwordx4 v[214:215], off
	v_lshl_add_u64 v[214:215], s[4:5], 0, v[134:135]
	s_add_i32 m0, s30, 0x2000
	s_nop 0
	global_load_lds_dwordx4 v[214:215], off
	v_lshl_add_u64 v[214:215], v[218:219], 0, s[24:25]
	s_mov_b32 m0, s54
	s_nop 0
	global_load_lds_dwordx4 v[214:215], off
	v_lshl_add_u64 v[214:215], v[220:221], 0, s[24:25]
	s_mov_b32 m0, s55
	s_nop 0
	global_load_lds_dwordx4 v[214:215], off
	s_waitcnt vmcnt(8)
	s_waitcnt lgkmcnt(0)
	s_barrier
	s_setprio 1
	v_mfma_f32_16x16x32_bf16 v[62:65], v[142:145], v[174:177], v[62:65]
	v_mfma_f32_16x16x32_bf16 v[62:65], v[146:149], v[178:181], v[62:65]
	v_mfma_f32_16x16x32_bf16 v[58:61], v[150:153], v[174:177], v[58:61]
	v_mfma_f32_16x16x32_bf16 v[58:61], v[154:157], v[178:181], v[58:61]
	v_mfma_f32_16x16x32_bf16 v[46:49], v[142:145], v[182:185], v[46:49]
	v_mfma_f32_16x16x32_bf16 v[46:49], v[146:149], v[186:189], v[46:49]
	v_mfma_f32_16x16x32_bf16 v[42:45], v[150:153], v[182:185], v[42:45]
	v_mfma_f32_16x16x32_bf16 v[42:45], v[154:157], v[186:189], v[42:45]
	v_mfma_f32_16x16x32_bf16 v[30:33], v[142:145], v[190:193], v[30:33]
	v_mfma_f32_16x16x32_bf16 v[30:33], v[146:149], v[194:197], v[30:33]
	v_mfma_f32_16x16x32_bf16 v[26:29], v[150:153], v[190:193], v[26:29]
	v_mfma_f32_16x16x32_bf16 v[26:29], v[154:157], v[194:197], v[26:29]
	v_mfma_f32_16x16x32_bf16 v[14:17], v[142:145], v[198:201], v[14:17]
	v_mfma_f32_16x16x32_bf16 v[14:17], v[146:149], v[202:205], v[14:17]
	v_mfma_f32_16x16x32_bf16 v[10:13], v[150:153], v[198:201], v[10:13]
	v_mfma_f32_16x16x32_bf16 v[10:13], v[154:157], v[202:205], v[10:13]
	v_mfma_f32_16x16x32_bf16 v[54:57], v[158:161], v[174:177], v[54:57]
	v_mfma_f32_16x16x32_bf16 v[54:57], v[162:165], v[178:181], v[54:57]
	v_mfma_f32_16x16x32_bf16 v[50:53], v[166:169], v[174:177], v[50:53]
	v_mfma_f32_16x16x32_bf16 v[50:53], v[170:173], v[178:181], v[50:53]
	v_mfma_f32_16x16x32_bf16 v[38:41], v[158:161], v[182:185], v[38:41]
	v_mfma_f32_16x16x32_bf16 v[38:41], v[162:165], v[186:189], v[38:41]
	v_mfma_f32_16x16x32_bf16 v[34:37], v[166:169], v[182:185], v[34:37]
	v_mfma_f32_16x16x32_bf16 v[34:37], v[170:173], v[186:189], v[34:37]
	v_mfma_f32_16x16x32_bf16 v[22:25], v[158:161], v[190:193], v[22:25]
	v_mfma_f32_16x16x32_bf16 v[22:25], v[162:165], v[194:197], v[22:25]
	v_mfma_f32_16x16x32_bf16 v[18:21], v[166:169], v[190:193], v[18:21]
	v_mfma_f32_16x16x32_bf16 v[18:21], v[170:173], v[194:197], v[18:21]
	s_setprio 2
	s_barrier
	v_mfma_f32_16x16x32_bf16 v[6:9], v[158:161], v[198:201], v[6:9]
	v_mfma_f32_16x16x32_bf16 v[6:9], v[162:165], v[202:205], v[6:9]
	v_mfma_f32_16x16x32_bf16 v[2:5], v[166:169], v[198:201], v[2:5]
	v_mfma_f32_16x16x32_bf16 v[2:5], v[170:173], v[202:205], v[2:5]
	s_setprio 0
	s_nop 0
	s_add_i32 s58, s58, 2
	s_add_u32 s56, s56, 0x100
	s_addc_u32 s57, s57, 0
	s_add_u32 s2, s2, 0x100
	s_addc_u32 s3, s3, 0
	v_lshl_add_u64 v[136:137], v[136:137], 0, s[28:29]
	s_cmp_lt_u32 s58, 42
	v_lshl_add_u64 v[138:139], v[138:139], 0, s[28:29]
.LBB0_1018:
	s_add_u32 s4, s70, s56
	s_addc_u32 s5, s71, s57
	s_add_u32 s59, s70, s2
	s_addc_u32 s60, s71, s3
	s_add_i32 s61, 0, 0x10000
	s_cmp_eq_u32 s58, 40
	s_cselect_b32 s31, s1, s5
	s_cselect_b32 s30, s0, s4
	s_cselect_b32 s5, s15, s60
	s_cselect_b32 s4, s14, s59
	s_add_i32 s59, 0, 0x14000
	v_add_u32_e32 v154, s61, v140
	v_add_u32_e32 v170, s59, v140
	ds_read_b128 v[142:145], v154
	ds_read_b128 v[146:149], v154 offset:1024
	ds_read_b128 v[150:153], v154 offset:2048
	ds_read_b128 v[154:157], v154 offset:3072
	ds_read_b128 v[158:161], v170
	ds_read_b128 v[162:165], v170 offset:1024
	ds_read_b128 v[166:169], v170 offset:2048
	ds_read_b128 v[170:173], v170 offset:3072
	v_lshl_add_u64 v[214:215], s[70:71], 0, v[136:137]
	s_add_i32 m0, s50, 0xc000
	ds_read_b128 v[174:177], v141
	ds_read_b128 v[178:181], v141 offset:1024
	ds_read_b128 v[182:185], v141 offset:2048
	ds_read_b128 v[186:189], v141 offset:3072
	ds_read_b128 v[190:193], v141 offset:4096
	ds_read_b128 v[194:197], v141 offset:5120
	ds_read_b128 v[198:201], v141 offset:6144
	ds_read_b128 v[202:205], v141 offset:7168
	global_load_lds_dwordx4 v[214:215], off
	v_lshl_add_u64 v[214:215], s[70:71], 0, v[138:139]
	s_add_i32 m0, s50, 0xe000
	s_nop 0
	global_load_lds_dwordx4 v[214:215], off
	s_waitcnt vmcnt(8)
	s_waitcnt lgkmcnt(0)
	s_barrier
	s_setprio 1
	v_mfma_f32_16x16x32_bf16 v[126:129], v[142:145], v[174:177], v[126:129]
	v_mfma_f32_16x16x32_bf16 v[126:129], v[146:149], v[178:181], v[126:129]
	v_mfma_f32_16x16x32_bf16 v[122:125], v[150:153], v[174:177], v[122:125]
	v_mfma_f32_16x16x32_bf16 v[122:125], v[154:157], v[178:181], v[122:125]
	v_mfma_f32_16x16x32_bf16 v[110:113], v[142:145], v[182:185], v[110:113]
	v_mfma_f32_16x16x32_bf16 v[110:113], v[146:149], v[186:189], v[110:113]
	v_mfma_f32_16x16x32_bf16 v[106:109], v[150:153], v[182:185], v[106:109]
	v_mfma_f32_16x16x32_bf16 v[106:109], v[154:157], v[186:189], v[106:109]
	v_mfma_f32_16x16x32_bf16 v[94:97], v[142:145], v[190:193], v[94:97]
	v_mfma_f32_16x16x32_bf16 v[94:97], v[146:149], v[194:197], v[94:97]
	v_mfma_f32_16x16x32_bf16 v[90:93], v[150:153], v[190:193], v[90:93]
	v_mfma_f32_16x16x32_bf16 v[90:93], v[154:157], v[194:197], v[90:93]
	v_mfma_f32_16x16x32_bf16 v[78:81], v[142:145], v[198:201], v[78:81]
	v_mfma_f32_16x16x32_bf16 v[78:81], v[146:149], v[202:205], v[78:81]
	v_mfma_f32_16x16x32_bf16 v[74:77], v[150:153], v[198:201], v[74:77]
	v_mfma_f32_16x16x32_bf16 v[74:77], v[154:157], v[202:205], v[74:77]
	v_mfma_f32_16x16x32_bf16 v[118:121], v[158:161], v[174:177], v[118:121]
	v_mfma_f32_16x16x32_bf16 v[118:121], v[162:165], v[178:181], v[118:121]
	v_mfma_f32_16x16x32_bf16 v[114:117], v[166:169], v[174:177], v[114:117]
	v_mfma_f32_16x16x32_bf16 v[114:117], v[170:173], v[178:181], v[114:117]
	v_mfma_f32_16x16x32_bf16 v[102:105], v[158:161], v[182:185], v[102:105]
	v_mfma_f32_16x16x32_bf16 v[102:105], v[162:165], v[186:189], v[102:105]
	v_mfma_f32_16x16x32_bf16 v[98:101], v[166:169], v[182:185], v[98:101]
	v_mfma_f32_16x16x32_bf16 v[98:101], v[170:173], v[186:189], v[98:101]
	v_mfma_f32_16x16x32_bf16 v[86:89], v[158:161], v[190:193], v[86:89]
	v_mfma_f32_16x16x32_bf16 v[86:89], v[162:165], v[194:197], v[86:89]
	v_mfma_f32_16x16x32_bf16 v[82:85], v[166:169], v[190:193], v[82:85]
	v_mfma_f32_16x16x32_bf16 v[82:85], v[170:173], v[194:197], v[82:85]
	s_setprio 2
	s_barrier
	v_mfma_f32_16x16x32_bf16 v[70:73], v[158:161], v[198:201], v[70:73]
	v_mfma_f32_16x16x32_bf16 v[70:73], v[162:165], v[202:205], v[70:73]
	v_mfma_f32_16x16x32_bf16 v[66:69], v[166:169], v[198:201], v[66:69]
	v_mfma_f32_16x16x32_bf16 v[66:69], v[170:173], v[202:205], v[66:69]
	s_setprio 0
	s_nop 0
	s_add_i32 s60, s61, s39
	v_lshl_add_u64 v[214:215], s[4:5], 0, v[130:131]
	s_mov_b32 m0, s60
	ds_read_b128 v[174:177], v141 offset:16384
	ds_read_b128 v[178:181], v141 offset:17408
	ds_read_b128 v[182:185], v141 offset:18432
	ds_read_b128 v[186:189], v141 offset:19456
	ds_read_b128 v[190:193], v141 offset:20480
	ds_read_b128 v[194:197], v141 offset:21504
	ds_read_b128 v[198:201], v141 offset:22528
	ds_read_b128 v[202:205], v141 offset:23552
	global_load_lds_dwordx4 v[214:215], off
	s_add_i32 m0, s60, 0x2000
	s_add_u32 s60, s4, 0xb0000
	v_lshl_add_u64 v[216:217], s[4:5], 0, v[134:135]
	s_addc_u32 s61, s5, 0
	s_add_i32 s59, s59, s39
	global_load_lds_dwordx4 v[216:217], off
	v_lshl_add_u64 v[218:219], s[60:61], 0, v[130:131]
	s_mov_b32 m0, s59
	v_lshl_add_u64 v[220:221], s[30:31], 0, v[134:135]
	global_load_lds_dwordx4 v[218:219], off
	v_lshl_add_u64 v[218:219], s[60:61], 0, v[134:135]
	s_add_i32 m0, s59, 0x2000
	s_nop 0
	global_load_lds_dwordx4 v[218:219], off
	v_lshl_add_u64 v[218:219], s[30:31], 0, v[130:131]
	s_mov_b32 m0, s50
	s_nop 0
	global_load_lds_dwordx4 v[218:219], off
	s_mov_b32 m0, s51
	s_nop 0
	global_load_lds_dwordx4 v[220:221], off
	s_waitcnt vmcnt(8)
	s_waitcnt lgkmcnt(0)
	s_barrier
	s_setprio 1
	v_mfma_f32_16x16x32_bf16 v[62:65], v[142:145], v[174:177], v[62:65]
	v_mfma_f32_16x16x32_bf16 v[62:65], v[146:149], v[178:181], v[62:65]
	v_mfma_f32_16x16x32_bf16 v[58:61], v[150:153], v[174:177], v[58:61]
	v_mfma_f32_16x16x32_bf16 v[58:61], v[154:157], v[178:181], v[58:61]
	v_mfma_f32_16x16x32_bf16 v[46:49], v[142:145], v[182:185], v[46:49]
	v_mfma_f32_16x16x32_bf16 v[46:49], v[146:149], v[186:189], v[46:49]
	v_mfma_f32_16x16x32_bf16 v[42:45], v[150:153], v[182:185], v[42:45]
	v_mfma_f32_16x16x32_bf16 v[42:45], v[154:157], v[186:189], v[42:45]
	v_mfma_f32_16x16x32_bf16 v[30:33], v[142:145], v[190:193], v[30:33]
	v_mfma_f32_16x16x32_bf16 v[30:33], v[146:149], v[194:197], v[30:33]
	v_mfma_f32_16x16x32_bf16 v[26:29], v[150:153], v[190:193], v[26:29]
	v_mfma_f32_16x16x32_bf16 v[26:29], v[154:157], v[194:197], v[26:29]
	v_mfma_f32_16x16x32_bf16 v[14:17], v[142:145], v[198:201], v[14:17]
	v_mfma_f32_16x16x32_bf16 v[14:17], v[146:149], v[202:205], v[14:17]
	v_mfma_f32_16x16x32_bf16 v[10:13], v[150:153], v[198:201], v[10:13]
	v_mfma_f32_16x16x32_bf16 v[10:13], v[154:157], v[202:205], v[10:13]
	v_mfma_f32_16x16x32_bf16 v[54:57], v[158:161], v[174:177], v[54:57]
	v_mfma_f32_16x16x32_bf16 v[54:57], v[162:165], v[178:181], v[54:57]
	v_mfma_f32_16x16x32_bf16 v[50:53], v[166:169], v[174:177], v[50:53]
	v_mfma_f32_16x16x32_bf16 v[50:53], v[170:173], v[178:181], v[50:53]
	v_mfma_f32_16x16x32_bf16 v[38:41], v[158:161], v[182:185], v[38:41]
	v_mfma_f32_16x16x32_bf16 v[38:41], v[162:165], v[186:189], v[38:41]
	v_mfma_f32_16x16x32_bf16 v[34:37], v[166:169], v[182:185], v[34:37]
	v_mfma_f32_16x16x32_bf16 v[34:37], v[170:173], v[186:189], v[34:37]
	v_mfma_f32_16x16x32_bf16 v[22:25], v[158:161], v[190:193], v[22:25]
	v_mfma_f32_16x16x32_bf16 v[22:25], v[162:165], v[194:197], v[22:25]
	v_mfma_f32_16x16x32_bf16 v[18:21], v[166:169], v[190:193], v[18:21]
	v_mfma_f32_16x16x32_bf16 v[18:21], v[170:173], v[194:197], v[18:21]
	s_setprio 2
	s_barrier
	v_mfma_f32_16x16x32_bf16 v[6:9], v[158:161], v[198:201], v[6:9]
	v_mfma_f32_16x16x32_bf16 v[6:9], v[162:165], v[202:205], v[6:9]
	v_mfma_f32_16x16x32_bf16 v[2:5], v[166:169], v[198:201], v[2:5]
	v_mfma_f32_16x16x32_bf16 v[2:5], v[170:173], v[202:205], v[2:5]
	s_setprio 0
	s_nop 0
	s_add_i32 s59, 0, 0x18000
	s_add_i32 s60, 0, 0x1c000
	v_add_u32_e32 v154, s59, v140
	v_add_u32_e32 v170, s60, v140
	ds_read_b128 v[142:145], v154
	ds_read_b128 v[146:149], v154 offset:1024
	ds_read_b128 v[150:153], v154 offset:2048
	ds_read_b128 v[154:157], v154 offset:3072
	ds_read_b128 v[158:161], v170
	ds_read_b128 v[162:165], v170 offset:1024
	ds_read_b128 v[166:169], v170 offset:2048
	ds_read_b128 v[170:173], v170 offset:3072
	s_add_u32 s30, s30, 0xb0000
	s_addc_u32 s31, s31, 0
	s_mov_b32 m0, s52
	v_lshl_add_u64 v[222:223], s[30:31], 0, v[130:131]
	ds_read_b128 v[174:177], v141 offset:32768
	ds_read_b128 v[178:181], v141 offset:33792
	ds_read_b128 v[182:185], v141 offset:34816
	ds_read_b128 v[186:189], v141 offset:35840
	ds_read_b128 v[190:193], v141 offset:36864
	ds_read_b128 v[194:197], v141 offset:37888
	ds_read_b128 v[198:201], v141 offset:38912
	ds_read_b128 v[202:205], v141 offset:39936
	global_load_lds_dwordx4 v[222:223], off
	v_lshl_add_u64 v[222:223], s[30:31], 0, v[134:135]
	s_mov_b32 m0, s53
	s_nop 0
	global_load_lds_dwordx4 v[222:223], off
	s_waitcnt vmcnt(8)
	s_waitcnt lgkmcnt(0)
	s_barrier
	s_setprio 1
	v_mfma_f32_16x16x32_bf16 v[126:129], v[142:145], v[174:177], v[126:129]
	v_mfma_f32_16x16x32_bf16 v[126:129], v[146:149], v[178:181], v[126:129]
	v_mfma_f32_16x16x32_bf16 v[122:125], v[150:153], v[174:177], v[122:125]
	v_mfma_f32_16x16x32_bf16 v[122:125], v[154:157], v[178:181], v[122:125]
	v_mfma_f32_16x16x32_bf16 v[110:113], v[142:145], v[182:185], v[110:113]
	v_mfma_f32_16x16x32_bf16 v[110:113], v[146:149], v[186:189], v[110:113]
	v_mfma_f32_16x16x32_bf16 v[106:109], v[150:153], v[182:185], v[106:109]
	v_mfma_f32_16x16x32_bf16 v[106:109], v[154:157], v[186:189], v[106:109]
	v_mfma_f32_16x16x32_bf16 v[94:97], v[142:145], v[190:193], v[94:97]
	v_mfma_f32_16x16x32_bf16 v[94:97], v[146:149], v[194:197], v[94:97]
	v_mfma_f32_16x16x32_bf16 v[90:93], v[150:153], v[190:193], v[90:93]
	v_mfma_f32_16x16x32_bf16 v[90:93], v[154:157], v[194:197], v[90:93]
	v_mfma_f32_16x16x32_bf16 v[78:81], v[142:145], v[198:201], v[78:81]
	v_mfma_f32_16x16x32_bf16 v[78:81], v[146:149], v[202:205], v[78:81]
	v_mfma_f32_16x16x32_bf16 v[74:77], v[150:153], v[198:201], v[74:77]
	v_mfma_f32_16x16x32_bf16 v[74:77], v[154:157], v[202:205], v[74:77]
	v_mfma_f32_16x16x32_bf16 v[118:121], v[158:161], v[174:177], v[118:121]
	v_mfma_f32_16x16x32_bf16 v[118:121], v[162:165], v[178:181], v[118:121]
	v_mfma_f32_16x16x32_bf16 v[114:117], v[166:169], v[174:177], v[114:117]
	v_mfma_f32_16x16x32_bf16 v[114:117], v[170:173], v[178:181], v[114:117]
	v_mfma_f32_16x16x32_bf16 v[102:105], v[158:161], v[182:185], v[102:105]
	v_mfma_f32_16x16x32_bf16 v[102:105], v[162:165], v[186:189], v[102:105]
	v_mfma_f32_16x16x32_bf16 v[98:101], v[166:169], v[182:185], v[98:101]
	v_mfma_f32_16x16x32_bf16 v[98:101], v[170:173], v[186:189], v[98:101]
	v_mfma_f32_16x16x32_bf16 v[86:89], v[158:161], v[190:193], v[86:89]
	v_mfma_f32_16x16x32_bf16 v[86:89], v[162:165], v[194:197], v[86:89]
	v_mfma_f32_16x16x32_bf16 v[82:85], v[166:169], v[190:193], v[82:85]
	v_mfma_f32_16x16x32_bf16 v[82:85], v[170:173], v[194:197], v[82:85]
	s_setprio 2
	s_barrier
	v_mfma_f32_16x16x32_bf16 v[70:73], v[158:161], v[198:201], v[70:73]
	v_mfma_f32_16x16x32_bf16 v[70:73], v[162:165], v[202:205], v[70:73]
	v_mfma_f32_16x16x32_bf16 v[66:69], v[166:169], v[198:201], v[66:69]
	v_mfma_f32_16x16x32_bf16 v[66:69], v[170:173], v[202:205], v[66:69]
	s_setprio 0
	s_nop 0
	s_add_i32 s30, s59, s39
	v_lshl_add_u64 v[214:215], v[214:215], 0, s[24:25]
	s_mov_b32 m0, s30
	ds_read_b128 v[174:177], v141 offset:49152
	ds_read_b128 v[178:181], v141 offset:50176
	ds_read_b128 v[182:185], v141 offset:51200
	ds_read_b128 v[186:189], v141 offset:52224
	ds_read_b128 v[190:193], v141 offset:53248
	ds_read_b128 v[194:197], v141 offset:54272
	ds_read_b128 v[198:201], v141 offset:55296
	ds_read_b128 v[202:205], v141 offset:56320
	global_load_lds_dwordx4 v[214:215], off
	s_add_i32 m0, s30, 0x2000
	s_add_u32 s4, s4, 0xb0080
	v_lshl_add_u64 v[214:215], v[216:217], 0, s[24:25]
	s_addc_u32 s5, s5, 0
	s_add_i32 s30, s60, s39
	global_load_lds_dwordx4 v[214:215], off
	v_lshl_add_u64 v[214:215], s[4:5], 0, v[130:131]
	s_mov_b32 m0, s30
	s_nop 0
	global_load_lds_dwordx4 v[214:215], off
	v_lshl_add_u64 v[214:215], s[4:5], 0, v[134:135]
	s_add_i32 m0, s30, 0x2000
	s_nop 0
	global_load_lds_dwordx4 v[214:215], off
	v_lshl_add_u64 v[214:215], v[218:219], 0, s[24:25]
	s_mov_b32 m0, s54
	s_nop 0
	global_load_lds_dwordx4 v[214:215], off
	v_lshl_add_u64 v[214:215], v[220:221], 0, s[24:25]
	s_mov_b32 m0, s55
	s_nop 0
	global_load_lds_dwordx4 v[214:215], off
	s_waitcnt vmcnt(8)
	s_waitcnt lgkmcnt(0)
	s_barrier
	s_setprio 1
	v_mfma_f32_16x16x32_bf16 v[62:65], v[142:145], v[174:177], v[62:65]
	v_mfma_f32_16x16x32_bf16 v[62:65], v[146:149], v[178:181], v[62:65]
	v_mfma_f32_16x16x32_bf16 v[58:61], v[150:153], v[174:177], v[58:61]
	v_mfma_f32_16x16x32_bf16 v[58:61], v[154:157], v[178:181], v[58:61]
	v_mfma_f32_16x16x32_bf16 v[46:49], v[142:145], v[182:185], v[46:49]
	v_mfma_f32_16x16x32_bf16 v[46:49], v[146:149], v[186:189], v[46:49]
	v_mfma_f32_16x16x32_bf16 v[42:45], v[150:153], v[182:185], v[42:45]
	v_mfma_f32_16x16x32_bf16 v[42:45], v[154:157], v[186:189], v[42:45]
	v_mfma_f32_16x16x32_bf16 v[30:33], v[142:145], v[190:193], v[30:33]
	v_mfma_f32_16x16x32_bf16 v[30:33], v[146:149], v[194:197], v[30:33]
	v_mfma_f32_16x16x32_bf16 v[26:29], v[150:153], v[190:193], v[26:29]
	v_mfma_f32_16x16x32_bf16 v[26:29], v[154:157], v[194:197], v[26:29]
	v_mfma_f32_16x16x32_bf16 v[14:17], v[142:145], v[198:201], v[14:17]
	v_mfma_f32_16x16x32_bf16 v[14:17], v[146:149], v[202:205], v[14:17]
	v_mfma_f32_16x16x32_bf16 v[10:13], v[150:153], v[198:201], v[10:13]
	v_mfma_f32_16x16x32_bf16 v[10:13], v[154:157], v[202:205], v[10:13]
	v_mfma_f32_16x16x32_bf16 v[54:57], v[158:161], v[174:177], v[54:57]
	v_mfma_f32_16x16x32_bf16 v[54:57], v[162:165], v[178:181], v[54:57]
	v_mfma_f32_16x16x32_bf16 v[50:53], v[166:169], v[174:177], v[50:53]
	v_mfma_f32_16x16x32_bf16 v[50:53], v[170:173], v[178:181], v[50:53]
	v_mfma_f32_16x16x32_bf16 v[38:41], v[158:161], v[182:185], v[38:41]
	v_mfma_f32_16x16x32_bf16 v[38:41], v[162:165], v[186:189], v[38:41]
	v_mfma_f32_16x16x32_bf16 v[34:37], v[166:169], v[182:185], v[34:37]
	v_mfma_f32_16x16x32_bf16 v[34:37], v[170:173], v[186:189], v[34:37]
	v_mfma_f32_16x16x32_bf16 v[22:25], v[158:161], v[190:193], v[22:25]
	v_mfma_f32_16x16x32_bf16 v[22:25], v[162:165], v[194:197], v[22:25]
	v_mfma_f32_16x16x32_bf16 v[18:21], v[166:169], v[190:193], v[18:21]
	v_mfma_f32_16x16x32_bf16 v[18:21], v[170:173], v[194:197], v[18:21]
	s_setprio 2
	s_barrier
	v_mfma_f32_16x16x32_bf16 v[6:9], v[158:161], v[198:201], v[6:9]
	v_mfma_f32_16x16x32_bf16 v[6:9], v[162:165], v[202:205], v[6:9]
	v_mfma_f32_16x16x32_bf16 v[2:5], v[166:169], v[198:201], v[2:5]
	v_mfma_f32_16x16x32_bf16 v[2:5], v[170:173], v[202:205], v[2:5]
	s_setprio 0
	s_nop 0
	s_add_i32 s58, s58, 2
	s_add_u32 s56, s56, 0x100
	s_addc_u32 s57, s57, 0
	s_add_u32 s2, s2, 0x100
	s_addc_u32 s3, s3, 0
	v_lshl_add_u64 v[136:137], v[136:137], 0, s[28:29]
	s_cmp_lt_u32 s58, 42
	v_lshl_add_u64 v[138:139], v[138:139], 0, s[28:29]
	s_cbranch_scc1 .LBB0_1018
	s_waitcnt vmcnt(0)
	s_cmpk_gt_u32 s36, 0xff
	s_cbranch_scc1 .LBB0_1021
	s_barrier
